# EpiConv: log2e folded into the conv table written by P0 (gate taps x log2e, value taps / log2e); 32 packed multiplies per wave-tile removed
# baseline (speedup 1.0000x reference)
; __global__ void __launch_bounds__(NTHREADS, 2) hymba_fwd(Args args) {
;     ...
;         for (int i = bx * NTHREADS + tid; i < 2 * DFF; i += G * NTHREADS) { const int l = i / DFF, c = i - l * DFF; const float* w = ap_->in[I_CW] + (size_t)l * 3 * NUP; const float* b = ap_->in[I_CB] + (size_t)l * NUP;
;             f32x4 a = {w[c], w[NUP + c], w[2 * NUP + c], b[c]}, g = {w[DFF + c], w[NUP + DFF + c], w[2 * NUP + DFF + c], b[DFF + c]}; *(f32x4*)(CT + (size_t)i * 8) = a; *(f32x4*)(CT + (size_t)i * 8 + 4) = g; }
.LBB0_94:
	v_mul_hi_i32 v1, v2, s13
	v_lshrrev_b32_e32 v3, 31, v1
	v_ashrrev_i32_e32 v1, 9, v1
	v_add_u32_e32 v1, v1, v3
	v_mad_i32_i24 v6, v1, s18, v2
	v_mul_hi_i32_i24_e32 v9, 0x10800, v1
	v_mul_i32_i24_e32 v8, 0x10800, v1
	v_ashrrev_i32_e32 v7, 31, v6
	v_lshl_add_u64 v[8:9], s[4:5], 0, v[8:9]
	v_lshlrev_b64 v[6:7], 2, v[6:7]
	v_lshl_add_u64 v[12:13], v[8:9], 0, v[6:7]
	v_add_co_u32_e32 v16, vcc, s19, v12
	v_mul_hi_i32_i24_e32 v11, 0x5800, v1
	s_nop 0
	v_addc_co_u32_e32 v17, vcc, 0, v13, vcc
	v_add_co_u32_e32 v18, vcc, s20, v12
	v_mul_i32_i24_e32 v10, 0x5800, v1
	s_nop 0
	v_addc_co_u32_e32 v19, vcc, 0, v13, vcc
	v_add_co_u32_e32 v20, vcc, s21, v12
	v_lshl_add_u64 v[10:11], s[6:7], 0, v[10:11]
	s_nop 0
	v_addc_co_u32_e32 v21, vcc, 0, v13, vcc
	v_add_co_u32_e32 v22, vcc, s22, v12
	v_lshl_add_u64 v[14:15], v[10:11], 0, v[6:7]
	s_nop 0
	v_addc_co_u32_e32 v23, vcc, 0, v13, vcc
	global_load_dword v9, v[14:15], off
	global_load_dword v6, v[12:13], off
	global_load_dword v7, v[16:17], off offset:2048
	global_load_dword v8, v[18:19], off
	global_load_dword v10, v[20:21], off offset:3072
	v_add_co_u32_e32 v16, vcc, s23, v12
	v_add_u32_e32 v2, s12, v2
	s_nop 0
	v_addc_co_u32_e32 v17, vcc, 0, v13, vcc
	v_add_co_u32_e32 v14, vcc, s21, v14
	global_load_dword v11, v[22:23], off offset:1024
	global_load_dword v12, v[16:17], off offset:3072
	v_addc_co_u32_e32 v15, vcc, 0, v15, vcc
	global_load_dword v13, v[14:15], off offset:3072
	v_cmp_lt_i32_e32 vcc, s24, v2
	s_or_b64 s[16:17], vcc, s[16:17]
	s_waitcnt vmcnt(4)
	v_mul_f32_e32 v6, 0x3f317218, v6
	v_mul_f32_e32 v7, 0x3f317218, v7
	v_mul_f32_e32 v8, 0x3f317218, v8
	v_mul_f32_e32 v9, 0x3f317218, v9
	global_store_dwordx4 v[4:5], v[6:9], off
	s_waitcnt vmcnt(1)
	v_mul_f32_e32 v10, 0x3fb8aa3b, v10
	v_mul_f32_e32 v11, 0x3fb8aa3b, v11
	v_mul_f32_e32 v12, 0x3fb8aa3b, v12
	v_mul_f32_e32 v13, 0x3fb8aa3b, v13
	global_store_dwordx4 v[4:5], v[10:13], off offset:16
	v_lshl_add_u64 v[4:5], v[4:5], 0, s[14:15]
	s_andn2_b64 exec, exec, s[16:17]
	s_cbranch_execnz .LBB0_94

;     __device__ __forceinline__ void operator()(const f32x4 (&acc)[2][2][4][2], const Unit& u, int wr, int wc, int fr, int fq) const {
;         int seqbase, t0, slen; halo_decode(u.pm, seqbase, t0, slen);
;         const f32x4* ct = (const f32x4*)(CT + (size_t)(128 * u.pn) * 8) + (32 * wc + 8 * fq) * 2;
;         const bool f0 = (fr == 0), f15 = (fr == 15);
; #pragma unroll
;         for (int ai = 0; ai < 2; ++ai) {
;             const int tbase = t0 + 62 * (2 * ai + wr) - 1;
;             float rs[4];
; #pragma unroll
;             for (int m = 0; m < 4; ++m) { const int t = tbase + 16 * m + fr; const bool vin = (t >= 0) && (t < slen); const int grow = seqbase + (vin ? t : 0);
;                 const f32x4 p = *(const f32x4*)(PS + (size_t)grow * 16 + 4 * fq); float s = (p[0] + p[1]) + (p[2] + p[3]); s = bfly_add<16>(s); s = bfly_add<32>(s); rs[m] = vin ? rsqrtf(s * (1.f / DM) + EPS) : 0.f; }
;             unsigned outw[4][2][2];
; #pragma unroll
;             for (int n = 0; n < 2; ++n)
; #pragma unroll
;                 for (int jp = 0; jp < 2; ++jp) {
;                     const int cidx = (4 * n + 2 * jp) * 2;
;                     const f32x4 c0a = ct[cidx], c0b = ct[cidx + 1], c1a = ct[cidx + 2], c1b = ct[cidx + 3];
.LBB0_794:
	s_mul_i32 s52, s14, 0xf8
	s_add_i32 s52, s52, s49
	v_add_u32_e32 v190, s52, v161
	v_cmp_gt_u32_e32 vcc, s51, v190
	s_lshl_b32 s36, s33, 7
	s_ashr_i32 s37, s36, 31
	v_cndmask_b32_e32 v128, 0, v190, vcc
	v_add_u32_e32 v128, s29, v128
	v_ashrrev_i32_e32 v129, 31, v128
	v_lshlrev_b64 v[128:129], 6, v[128:129]
	v_lshl_add_u64 v[128:129], v[164:165], 0, v[128:129]
	global_load_dwordx4 v[128:131], v[128:129], off
	s_lshl_b64 s[2:3], s[36:37], 5
	v_lshl_add_u64 v[170:171], v[162:163], 0, s[2:3]
	s_waitcnt vmcnt(0)
	v_mov_b32_e32 v132, v129
	v_mov_b32_e32 v133, v130
	v_mov_b32_e32 v129, v131
	v_pk_add_f32 v[128:129], v[132:133], v[128:129]
	s_nop 0
	v_add_f32_e32 v128, v128, v129
	v_mov_b32_e32 v129, v128
	s_nop 1
	v_permlane16_swap_b32_e32 v128, v129
	s_waitcnt lgkmcnt(0)
	v_add_f32_e32 v133, v128, v129
	v_add_u32_e32 v128, 16, v190
	v_cmp_gt_u32_e64 s[14:15], s51, v128
	v_mov_b32_e32 v135, v133
	s_nop 1
	v_permlane32_swap_b32_e32 v133, v135
	v_cndmask_b32_e64 v128, 0, v128, s[14:15]
	v_add_u32_e32 v128, s29, v128
	v_ashrrev_i32_e32 v129, 31, v128
	v_lshlrev_b64 v[128:129], 6, v[128:129]
	v_lshl_add_u64 v[128:129], v[164:165], 0, v[128:129]
	global_load_dwordx4 v[128:131], v[128:129], off
	s_waitcnt vmcnt(0)
	v_mov_b32_e32 v136, v129
	v_mov_b32_e32 v137, v130
	v_mov_b32_e32 v129, v131
	v_pk_add_f32 v[128:129], v[136:137], v[128:129]
	s_nop 0
	v_add_f32_e32 v128, v128, v129
	v_mov_b32_e32 v129, v128
	s_nop 1
	v_permlane16_swap_b32_e32 v128, v129
	s_waitcnt lgkmcnt(0)
	v_add_f32_e32 v132, v128, v129
	v_mov_b32_e32 v134, v132
	s_nop 1
	v_permlane32_swap_b32_e32 v132, v134
	v_pk_add_f32 v[128:129], v[132:133], v[134:135]
	v_mov_b64_e32 v[132:133], s[78:79]
	v_pk_fma_f32 v[128:129], v[128:129], s[82:83], v[132:133] op_sel_hi:[1,0,0]
	s_nop 0
	v_mul_f32_e32 v130, 0x4b800000, v129
	v_cmp_gt_f32_e64 s[20:21], s62, v129
	v_cmp_gt_f32_e64 s[18:19], s62, v128
	s_nop 0
	v_cndmask_b32_e64 v129, v129, v130, s[20:21]
	v_rsq_f32_e32 v129, v129
	s_nop 0
	v_mul_f32_e32 v130, 0x45800000, v129
	v_cndmask_b32_e64 v129, v129, v130, s[20:21]
	v_cndmask_b32_e32 v172, 0, v129, vcc
	v_mul_f32_e32 v129, 0x4b800000, v128
	v_cndmask_b32_e64 v128, v128, v129, s[18:19]
	v_rsq_f32_e32 v128, v128
	s_nop 0
	v_mul_f32_e32 v129, 0x45800000, v128
	v_cndmask_b32_e64 v128, v128, v129, s[18:19]
	v_cndmask_b32_e64 v144, 0, v128, s[14:15]
	v_add_u32_e32 v128, 32, v190
	v_cmp_gt_u32_e32 vcc, s51, v128
	s_nop 1
	v_cndmask_b32_e32 v128, 0, v128, vcc
	v_add_u32_e32 v128, s29, v128
	v_ashrrev_i32_e32 v129, 31, v128
	v_lshlrev_b64 v[128:129], 6, v[128:129]
	v_lshl_add_u64 v[128:129], v[164:165], 0, v[128:129]
	global_load_dwordx4 v[128:131], v[128:129], off
	s_waitcnt vmcnt(0)
	v_mov_b32_e32 v134, v129
	v_mov_b32_e32 v135, v130
	v_mov_b32_e32 v129, v131
	v_pk_add_f32 v[128:129], v[134:135], v[128:129]
	s_nop 0
	v_add_f32_e32 v128, v128, v129
	v_mov_b32_e32 v129, v128
	s_nop 1
	v_permlane16_swap_b32_e32 v128, v129
	s_waitcnt lgkmcnt(0)
	v_add_f32_e32 v135, v128, v129
	v_add_u32_e32 v128, 48, v190
	v_cmp_gt_u32_e64 s[14:15], s51, v128
	v_mov_b32_e32 v137, v135
	s_nop 1
	v_permlane32_swap_b32_e32 v135, v137
	v_cndmask_b32_e64 v128, 0, v128, s[14:15]
	v_add_u32_e32 v128, s29, v128
	v_ashrrev_i32_e32 v129, 31, v128
	v_lshlrev_b64 v[128:129], 6, v[128:129]
	v_lshl_add_u64 v[128:129], v[164:165], 0, v[128:129]
	global_load_dwordx4 v[128:131], v[128:129], off
	s_waitcnt vmcnt(0)
	v_mov_b32_e32 v138, v129
	v_mov_b32_e32 v139, v130
	v_mov_b32_e32 v129, v131
	v_pk_add_f32 v[128:129], v[138:139], v[128:129]
	s_nop 0
	v_add_f32_e32 v128, v128, v129
	v_mov_b32_e32 v129, v128
	s_nop 1
	v_permlane16_swap_b32_e32 v128, v129
	s_waitcnt lgkmcnt(0)
	v_add_f32_e32 v134, v128, v129
	v_mov_b32_e32 v136, v134
	s_nop 1
	v_permlane32_swap_b32_e32 v134, v136
	v_pk_add_f32 v[128:129], v[134:135], v[136:137]
	s_nop 0
	v_pk_fma_f32 v[128:129], v[128:129], s[82:83], v[132:133] op_sel_hi:[1,0,0]
	s_nop 0
	v_mul_f32_e32 v130, 0x4b800000, v129
	v_cmp_gt_f32_e64 s[20:21], s62, v129
	v_cmp_gt_f32_e64 s[18:19], s62, v128
	s_nop 0
	v_cndmask_b32_e64 v129, v129, v130, s[20:21]
	v_rsq_f32_e32 v129, v129
	s_nop 0
	v_mul_f32_e32 v130, 0x45800000, v129
	v_cndmask_b32_e64 v129, v129, v130, s[20:21]
	v_cndmask_b32_e32 v174, 0, v129, vcc
	v_mul_f32_e32 v129, 0x4b800000, v128
	v_cndmask_b32_e64 v128, v128, v129, s[18:19]
	v_rsq_f32_e32 v128, v128
	s_nop 0
	v_mul_f32_e32 v129, 0x45800000, v128
	v_cndmask_b32_e64 v128, v128, v129, s[18:19]
	v_cndmask_b32_e64 v176, 0, v128, s[14:15]
	global_load_dwordx4 v[132:135], v[170:171], off offset:16
	global_load_dwordx4 v[128:131], v[170:171], off offset:48
	global_load_dwordx4 v[140:143], v[170:171], off
	global_load_dwordx4 v[136:139], v[170:171], off offset:32
	s_waitcnt vmcnt(3)
	v_mov_b32_e32 v178, v132
	v_pk_mul_f32 v[124:125], v[172:173], v[124:125] op_sel_hi:[0,1]
	v_pk_mul_f32 v[120:121], v[120:121], v[144:145] op_sel_hi:[1,0]
	s_waitcnt vmcnt(1)
	v_mov_b32_e32 v182, v140
	s_waitcnt vmcnt(0)
; __device__ __forceinline__ unsigned cvtpk(float lo, float hi) { f32x2 v = {lo, hi}; bf16x2_t b = __builtin_convertvector(v, bf16x2_t); return __builtin_bit_cast(unsigned, b); }
; __device__ __forceinline__ float dpp_ror1(float x) { return __builtin_bit_cast(float, __builtin_amdgcn_mov_dpp(__builtin_bit_cast(int, x), 0x121, 0xF, 0xF, true)); }
; __device__ __forceinline__ float dpp_ror15(float x) { return __builtin_bit_cast(float, __builtin_amdgcn_mov_dpp(__builtin_bit_cast(int, x), 0x12F, 0xF, 0xF, true)); }
;     __device__ __forceinline__ void operator()(const f32x4 (&acc)[2][2][4][2], const Unit& u, int wr, int wc, int fr, int fq) const {
;     ...
;                         for (int m = 0; m < 4; ++m) { uv[m] = uv[m] * rs[m]; rv[m] = (f32x2){dpp_ror1(uv[m][0]), dpp_ror1(uv[m][1])}; lv[m] = (f32x2){dpp_ror15(uv[m][0]), dpp_ror15(uv[m][1])}; }
; #pragma unroll
;                         for (int m = 0; m < 4; ++m) { const f32x2 pv_ = (m > 0 && f0) ? rv[m > 0 ? m - 1 : 0] : rv[m], nv_ = (m < 3 && f15) ? lv[m < 3 ? m + 1 : 3] : lv[m];
;                             cv[m] = bv + wv0 * pv_ + wv1 * uv[m] + wv2 * nv_; }
;                     }
;                     asm volatile("" : "+v"(cv[0]), "+v"(cv[1]), "+v"(cv[2]), "+v"(cv[3]));
;                     {
;                         f32x2 rg[4], lg[4];
; #pragma unroll
;                         for (int m = 0; m < 4; ++m) { ug[m] = ug[m] * rs[m]; rg[m] = (f32x2){dpp_ror1(ug[m][0]), dpp_ror1(ug[m][1])}; lg[m] = (f32x2){dpp_ror15(ug[m][0]), dpp_ror15(ug[m][1])}; }
; #pragma unroll
;                         for (int m = 0; m < 4; ++m) { const f32x2 pg_ = (m > 0 && f0) ? rg[m > 0 ? m - 1 : 0] : rg[m], ng_ = (m < 3 && f15) ? lg[m < 3 ? m + 1 : 3] : lg[m];
;                             const f32x2 cgt = bg + wg0 * pg_ + wg1 * ug[m] + wg2 * ng_;
;                             const f32x2 e = cgt * (-LOG2E);
;                             const f32x2 d = (f32x2){__builtin_amdgcn_exp2f(e[0]), __builtin_amdgcn_exp2f(e[1])} + 1.f;
;                             const f32x2 sg = {__builtin_amdgcn_rcpf(d[0]), __builtin_amdgcn_rcpf(d[1])};
;                             const f32x2 ov = cv[m] * cgt * sg;
;                             outw[m][n][jp] = cvtpk(ov[0], ov[1]); }
	v_mov_b32_e32 v183, v136
	v_mov_b32_e32 v193, v138
	v_mov_b32_e32 v179, v128
	v_mov_b32_e32 v128, v133
	v_mov_b32_dpp v132, v124 row_ror:1 row_mask:0xf bank_mask:0xf bound_ctrl:1
	v_mov_b32_dpp v133, v125 row_ror:1 row_mask:0xf bank_mask:0xf bound_ctrl:1
	v_mov_b32_dpp v191, v120 row_ror:1 row_mask:0xf bank_mask:0xf bound_ctrl:1
	v_mov_b32_dpp v196, v121 row_ror:1 row_mask:0xf bank_mask:0xf bound_ctrl:1
	v_mov_b32_e32 v138, v143
	v_pk_mul_f32 v[116:117], v[116:117], v[174:175] op_sel_hi:[1,0]
	v_pk_fma_f32 v[194:195], v[182:183], v[132:133], v[138:139]
	v_cndmask_b32_e64 v133, v196, v133, s[4:5]
	v_cndmask_b32_e64 v132, v191, v132, s[4:5]
	v_mov_b32_e32 v136, v141
	v_mov_b32_dpp v199, v116 row_ror:1 row_mask:0xf bank_mask:0xf bound_ctrl:1
	v_mov_b32_dpp v200, v117 row_ror:1 row_mask:0xf bank_mask:0xf bound_ctrl:1
	v_pk_fma_f32 v[132:133], v[182:183], v[132:133], v[138:139]
	v_mov_b32_dpp v197, v120 row_ror:15 row_mask:0xf bank_mask:0xf bound_ctrl:1
	v_mov_b32_dpp v198, v121 row_ror:15 row_mask:0xf bank_mask:0xf bound_ctrl:1
	v_pk_mul_f32 v[112:113], v[112:113], v[176:177] op_sel_hi:[1,0]
	v_pk_fma_f32 v[120:121], v[136:137], v[120:121], v[132:133]
	v_cndmask_b32_e64 v133, v200, v196, s[4:5]
	v_cndmask_b32_e64 v132, v199, v191, s[4:5]
	v_mov_b32_e32 v180, v134
	v_mov_b32_e32 v181, v130
	v_mov_b32_dpp v130, v124 row_ror:15 row_mask:0xf bank_mask:0xf bound_ctrl:1
	v_mov_b32_dpp v134, v125 row_ror:15 row_mask:0xf bank_mask:0xf bound_ctrl:1
	v_mov_b32_dpp v203, v112 row_ror:1 row_mask:0xf bank_mask:0xf bound_ctrl:1
	v_mov_b32_dpp v204, v113 row_ror:1 row_mask:0xf bank_mask:0xf bound_ctrl:1
	v_pk_fma_f32 v[132:133], v[182:183], v[132:133], v[138:139]
	v_mov_b32_e32 v192, v142
	v_mov_b32_dpp v201, v116 row_ror:15 row_mask:0xf bank_mask:0xf bound_ctrl:1
	v_mov_b32_dpp v202, v117 row_ror:15 row_mask:0xf bank_mask:0xf bound_ctrl:1
	v_cndmask_b32_e64 v143, v134, v198, s[6:7]
	v_cndmask_b32_e64 v142, v130, v197, s[6:7]
	v_pk_fma_f32 v[124:125], v[136:137], v[124:125], v[194:195]
	v_pk_fma_f32 v[116:117], v[136:137], v[116:117], v[132:133]
	v_cndmask_b32_e64 v133, v204, v200, s[4:5]
	v_cndmask_b32_e64 v132, v203, v199, s[4:5]
	v_mov_b32_dpp v140, v112 row_ror:15 row_mask:0xf bank_mask:0xf bound_ctrl:1
	v_mov_b32_dpp v141, v113 row_ror:15 row_mask:0xf bank_mask:0xf bound_ctrl:1
	v_pk_fma_f32 v[124:125], v[192:193], v[142:143], v[124:125]
	v_cndmask_b32_e64 v143, v198, v202, s[6:7]
	v_cndmask_b32_e64 v142, v197, v201, s[6:7]
	v_pk_fma_f32 v[132:133], v[182:183], v[132:133], v[138:139]
	v_pk_mul_f32 v[108:109], v[172:173], v[108:109] op_sel_hi:[0,1]
	v_pk_fma_f32 v[120:121], v[192:193], v[142:143], v[120:121]
	v_cndmask_b32_e64 v143, v202, v141, s[6:7]
	v_cndmask_b32_e64 v142, v201, v140, s[6:7]
	v_pk_fma_f32 v[112:113], v[136:137], v[112:113], v[132:133]
	v_mov_b32_dpp v132, v108 row_ror:1 row_mask:0xf bank_mask:0xf bound_ctrl:1
	v_mov_b32_dpp v133, v109 row_ror:1 row_mask:0xf bank_mask:0xf bound_ctrl:1
	v_pk_mul_f32 v[104:105], v[104:105], v[144:145] op_sel_hi:[1,0]
	v_mov_b32_e32 v130, v135
	v_pk_fma_f32 v[116:117], v[192:193], v[142:143], v[116:117]
	v_mov_b32_dpp v134, v108 row_ror:15 row_mask:0xf bank_mask:0xf bound_ctrl:1
	v_mov_b32_dpp v142, v109 row_ror:15 row_mask:0xf bank_mask:0xf bound_ctrl:1
	v_mov_b32_dpp v183, v104 row_ror:15 row_mask:0xf bank_mask:0xf bound_ctrl:1
	v_mov_b32_dpp v191, v105 row_ror:15 row_mask:0xf bank_mask:0xf bound_ctrl:1
	v_pk_mul_f32 v[136:137], v[100:101], v[174:175] op_sel_hi:[1,0]
	v_pk_fma_f32 v[100:101], v[178:179], v[132:133], v[130:131]
	v_pk_mul_f32 v[138:139], v[96:97], v[176:177] op_sel_hi:[1,0]
	v_cndmask_b32_e64 v97, v142, v191, s[6:7]
	v_cndmask_b32_e64 v96, v134, v183, s[6:7]
	v_pk_fma_f32 v[100:101], v[128:129], v[108:109], v[100:101]
	v_pk_fma_f32 v[112:113], v[192:193], v[140:141], v[112:113]
	v_pk_fma_f32 v[96:97], v[180:181], v[96:97], v[100:101]
	v_mov_b32_dpp v143, v104 row_ror:1 row_mask:0xf bank_mask:0xf bound_ctrl:1
	v_exp_f32_e64 v100, -v96
	v_exp_f32_e64 v101, -v97
	v_mov_b32_dpp v182, v105 row_ror:1 row_mask:0xf bank_mask:0xf bound_ctrl:1
	v_pk_mul_f32 v[96:97], v[124:125], v[96:97]
	v_mov_b32_dpp v194, v136 row_ror:15 row_mask:0xf bank_mask:0xf bound_ctrl:1
	v_mov_b32_dpp v195, v137 row_ror:15 row_mask:0xf bank_mask:0xf bound_ctrl:1
	v_pk_add_f32 v[100:101], v[100:101], 1.0 op_sel_hi:[1,0]
	v_cndmask_b32_e64 v109, v191, v195, s[6:7]
	v_rcp_f32_e32 v100, v100
	v_rcp_f32_e32 v101, v101
	v_cndmask_b32_e64 v108, v183, v194, s[6:7]
	v_mov_b32_dpp v192, v136 row_ror:1 row_mask:0xf bank_mask:0xf bound_ctrl:1
	v_mov_b32_dpp v193, v137 row_ror:1 row_mask:0xf bank_mask:0xf bound_ctrl:1
	v_pk_mul_f32 v[96:97], v[96:97], v[100:101]
	v_cndmask_b32_e64 v101, v182, v133, s[4:5]
	v_cndmask_b32_e64 v100, v143, v132, s[4:5]
	v_pk_fma_f32 v[100:101], v[178:179], v[100:101], v[130:131]
	v_mov_b32_dpp v140, v138 row_ror:15 row_mask:0xf bank_mask:0xf bound_ctrl:1
	v_pk_fma_f32 v[100:101], v[128:129], v[104:105], v[100:101]
	v_mov_b32_dpp v141, v139 row_ror:15 row_mask:0xf bank_mask:0xf bound_ctrl:1
	v_pk_fma_f32 v[100:101], v[180:181], v[108:109], v[100:101]
	v_cndmask_b32_e64 v109, v195, v141, s[6:7]
	v_exp_f32_e64 v104, -v100
	v_exp_f32_e64 v105, -v101
	v_pk_mul_f32 v[100:101], v[120:121], v[100:101]
	v_cndmask_b32_e64 v108, v194, v140, s[6:7]
	v_mov_b32_dpp v196, v138 row_ror:1 row_mask:0xf bank_mask:0xf bound_ctrl:1
	v_mov_b32_dpp v197, v139 row_ror:1 row_mask:0xf bank_mask:0xf bound_ctrl:1
	v_pk_add_f32 v[104:105], v[104:105], 1.0 op_sel_hi:[1,0]
	v_cvt_pk_bf16_f32 v96, v96, v97
	v_rcp_f32_e32 v104, v104
	v_rcp_f32_e32 v105, v105
	s_nop 0
	v_pk_mul_f32 v[100:101], v[100:101], v[104:105]
; __device__ __forceinline__ unsigned cvtpk(float lo, float hi) { f32x2 v = {lo, hi}; bf16x2_t b = __builtin_convertvector(v, bf16x2_t); return __builtin_bit_cast(unsigned, b); }
; __device__ __forceinline__ float dpp_ror1(float x) { return __builtin_bit_cast(float, __builtin_amdgcn_mov_dpp(__builtin_bit_cast(int, x), 0x121, 0xF, 0xF, true)); }
; __device__ __forceinline__ float dpp_ror15(float x) { return __builtin_bit_cast(float, __builtin_amdgcn_mov_dpp(__builtin_bit_cast(int, x), 0x12F, 0xF, 0xF, true)); }
;     __device__ __forceinline__ void operator()(const f32x4 (&acc)[2][2][4][2], const Unit& u, int wr, int wc, int fr, int fq) const {
;     ...
;                     {
;                         f32x2 rg[4], lg[4];
; #pragma unroll
;                         for (int m = 0; m < 4; ++m) { ug[m] = ug[m] * rs[m]; rg[m] = (f32x2){dpp_ror1(ug[m][0]), dpp_ror1(ug[m][1])}; lg[m] = (f32x2){dpp_ror15(ug[m][0]), dpp_ror15(ug[m][1])}; }
; #pragma unroll
;                         for (int m = 0; m < 4; ++m) { const f32x2 pg_ = (m > 0 && f0) ? rg[m > 0 ? m - 1 : 0] : rg[m], ng_ = (m < 3 && f15) ? lg[m < 3 ? m + 1 : 3] : lg[m];
;                             const f32x2 cgt = bg + wg0 * pg_ + wg1 * ug[m] + wg2 * ng_;
;                             const f32x2 e = cgt * (-LOG2E);
;                             const f32x2 d = (f32x2){__builtin_amdgcn_exp2f(e[0]), __builtin_amdgcn_exp2f(e[1])} + 1.f;
;                             const f32x2 sg = {__builtin_amdgcn_rcpf(d[0]), __builtin_amdgcn_rcpf(d[1])};
;                             const f32x2 ov = cv[m] * cgt * sg;
;                             outw[m][n][jp] = cvtpk(ov[0], ov[1]); }
	v_cndmask_b32_e64 v105, v193, v182, s[4:5]
	v_cndmask_b32_e64 v104, v192, v143, s[4:5]
	v_pk_fma_f32 v[104:105], v[178:179], v[104:105], v[130:131]
	v_cvt_pk_bf16_f32 v100, v100, v101
	v_pk_fma_f32 v[104:105], v[128:129], v[136:137], v[104:105]
	s_nop 0
	v_pk_fma_f32 v[104:105], v[180:181], v[108:109], v[104:105]
	s_nop 0
	v_exp_f32_e64 v108, -v104
	v_exp_f32_e64 v109, -v105
	v_pk_mul_f32 v[104:105], v[116:117], v[104:105]
	s_nop 0
	v_pk_add_f32 v[108:109], v[108:109], 1.0 op_sel_hi:[1,0]
	s_nop 0
	v_rcp_f32_e32 v108, v108
	v_rcp_f32_e32 v109, v109
	s_nop 0
	v_pk_mul_f32 v[104:105], v[104:105], v[108:109]
	v_cndmask_b32_e64 v109, v197, v193, s[4:5]
	v_cndmask_b32_e64 v108, v196, v192, s[4:5]
	v_pk_fma_f32 v[108:109], v[178:179], v[108:109], v[130:131]
	v_cvt_pk_bf16_f32 v104, v104, v105
	v_pk_fma_f32 v[108:109], v[128:129], v[138:139], v[108:109]
	s_nop 0
	v_pk_fma_f32 v[108:109], v[180:181], v[140:141], v[108:109]
	s_nop 0
	v_exp_f32_e64 v116, -v108
	v_exp_f32_e64 v117, -v109
	v_pk_mul_f32 v[108:109], v[112:113], v[108:109]
	s_nop 0
	v_pk_add_f32 v[116:117], v[116:117], 1.0 op_sel_hi:[1,0]
	s_nop 0
	v_rcp_f32_e32 v116, v116
	v_rcp_f32_e32 v117, v117
	s_nop 0
	v_pk_mul_f32 v[108:109], v[108:109], v[116:117]
	s_nop 0
	v_cvt_pk_bf16_f32 v108, v108, v109
	global_load_dwordx4 v[132:135], v[170:171], off offset:80
	global_load_dwordx4 v[128:131], v[170:171], off offset:112
	global_load_dwordx4 v[136:139], v[170:171], off offset:64
	global_load_dwordx4 v[140:143], v[170:171], off offset:96
	s_waitcnt vmcnt(3)
	v_mov_b32_e32 v116, v132
	v_pk_mul_f32 v[120:121], v[172:173], v[126:127] op_sel_hi:[0,1]
	s_waitcnt vmcnt(1)
	v_mov_b32_e32 v124, v136
	s_waitcnt vmcnt(0)
	v_mov_b32_e32 v125, v140
	v_mov_b32_e32 v179, v142
	v_mov_b32_e32 v117, v128
	v_mov_b32_e32 v128, v133
	v_mov_b32_dpp v126, v120 row_ror:1 row_mask:0xf bank_mask:0xf bound_ctrl:1
	v_mov_b32_dpp v127, v121 row_ror:1 row_mask:0xf bank_mask:0xf bound_ctrl:1
	v_pk_mul_f32 v[132:133], v[144:145], v[122:123] op_sel_hi:[0,1]
	v_mov_b32_e32 v142, v139
	v_mov_b32_e32 v178, v138
	v_mov_b32_e32 v112, v134
	v_mov_b32_e32 v113, v130
	v_mov_b32_e32 v140, v137
	v_mov_b32_dpp v97, v120 row_ror:15 row_mask:0xf bank_mask:0xf bound_ctrl:1
	v_mov_b32_dpp v101, v121 row_ror:15 row_mask:0xf bank_mask:0xf bound_ctrl:1
	v_mov_b32_dpp v130, v132 row_ror:15 row_mask:0xf bank_mask:0xf bound_ctrl:1
	v_mov_b32_dpp v134, v133 row_ror:15 row_mask:0xf bank_mask:0xf bound_ctrl:1
	v_pk_fma_f32 v[138:139], v[124:125], v[126:127], v[142:143]
	v_mov_b32_dpp v105, v132 row_ror:1 row_mask:0xf bank_mask:0xf bound_ctrl:1
	v_mov_b32_dpp v109, v133 row_ror:1 row_mask:0xf bank_mask:0xf bound_ctrl:1
	v_cndmask_b32_e64 v123, v101, v134, s[6:7]
	v_cndmask_b32_e64 v122, v97, v130, s[6:7]
	v_pk_fma_f32 v[120:121], v[140:141], v[120:121], v[138:139]
	v_pk_mul_f32 v[118:119], v[174:175], v[118:119] op_sel_hi:[0,1]
	v_pk_fma_f32 v[122:123], v[178:179], v[122:123], v[120:121]
	v_cndmask_b32_e64 v121, v109, v127, s[4:5]
	v_cndmask_b32_e64 v120, v105, v126, s[4:5]
	v_mov_b32_dpp v182, v118 row_ror:15 row_mask:0xf bank_mask:0xf bound_ctrl:1
	v_mov_b32_dpp v183, v119 row_ror:15 row_mask:0xf bank_mask:0xf bound_ctrl:1
	v_pk_fma_f32 v[120:121], v[124:125], v[120:121], v[142:143]
	v_mov_b32_dpp v180, v118 row_ror:1 row_mask:0xf bank_mask:0xf bound_ctrl:1
	v_mov_b32_dpp v181, v119 row_ror:1 row_mask:0xf bank_mask:0xf bound_ctrl:1
	v_cndmask_b32_e64 v127, v134, v183, s[6:7]
	v_cndmask_b32_e64 v126, v130, v182, s[6:7]
	v_pk_fma_f32 v[120:121], v[140:141], v[132:133], v[120:121]
	v_pk_mul_f32 v[114:115], v[176:177], v[114:115] op_sel_hi:[0,1]
	v_pk_fma_f32 v[120:121], v[178:179], v[126:127], v[120:121]
	v_cndmask_b32_e64 v127, v181, v109, s[4:5]
	v_cndmask_b32_e64 v126, v180, v105, s[4:5]
	v_mov_b32_dpp v191, v114 row_ror:1 row_mask:0xf bank_mask:0xf bound_ctrl:1
	v_mov_b32_dpp v192, v115 row_ror:1 row_mask:0xf bank_mask:0xf bound_ctrl:1
	v_pk_fma_f32 v[126:127], v[124:125], v[126:127], v[142:143]
	v_mov_b32_dpp v136, v114 row_ror:15 row_mask:0xf bank_mask:0xf bound_ctrl:1
	v_pk_fma_f32 v[118:119], v[140:141], v[118:119], v[126:127]
	v_cndmask_b32_e64 v127, v192, v181, s[4:5]
	v_cndmask_b32_e64 v126, v191, v180, s[4:5]
	v_pk_fma_f32 v[124:125], v[124:125], v[126:127], v[142:143]
	v_mov_b32_dpp v137, v115 row_ror:15 row_mask:0xf bank_mask:0xf bound_ctrl:1
	v_pk_fma_f32 v[114:115], v[140:141], v[114:115], v[124:125]
	v_pk_mul_f32 v[124:125], v[172:173], v[110:111] op_sel_hi:[0,1]
	v_pk_mul_f32 v[106:107], v[144:145], v[106:107] op_sel_hi:[0,1]
	v_mov_b32_e32 v130, v135
	v_mov_b32_dpp v110, v124 row_ror:1 row_mask:0xf bank_mask:0xf bound_ctrl:1
	v_mov_b32_dpp v111, v125 row_ror:1 row_mask:0xf bank_mask:0xf bound_ctrl:1
	v_cndmask_b32_e64 v133, v183, v137, s[6:7]
	v_cndmask_b32_e64 v132, v182, v136, s[6:7]
	v_pk_fma_f32 v[114:115], v[178:179], v[136:137], v[114:115]
	v_mov_b32_dpp v97, v124 row_ror:15 row_mask:0xf bank_mask:0xf bound_ctrl:1
	v_mov_b32_dpp v101, v125 row_ror:15 row_mask:0xf bank_mask:0xf bound_ctrl:1
	v_mov_b32_dpp v136, v106 row_ror:15 row_mask:0xf bank_mask:0xf bound_ctrl:1
	v_mov_b32_dpp v137, v107 row_ror:15 row_mask:0xf bank_mask:0xf bound_ctrl:1
	v_pk_fma_f32 v[134:135], v[116:117], v[110:111], v[130:131]
	v_pk_fma_f32 v[118:119], v[178:179], v[132:133], v[118:119]
	v_cndmask_b32_e64 v133, v101, v137, s[6:7]
	v_cndmask_b32_e64 v132, v97, v136, s[6:7]
	v_pk_fma_f32 v[124:125], v[128:129], v[124:125], v[134:135]
	v_mov_b32_dpp v105, v106 row_ror:1 row_mask:0xf bank_mask:0xf bound_ctrl:1
	v_pk_fma_f32 v[124:125], v[112:113], v[132:133], v[124:125]
	v_mov_b32_dpp v109, v107 row_ror:1 row_mask:0xf bank_mask:0xf bound_ctrl:1
; __device__ __forceinline__ unsigned cvtpk(float lo, float hi) { f32x2 v = {lo, hi}; bf16x2_t b = __builtin_convertvector(v, bf16x2_t); return __builtin_bit_cast(unsigned, b); }
; __device__ __forceinline__ float dpp_ror1(float x) { return __builtin_bit_cast(float, __builtin_amdgcn_mov_dpp(__builtin_bit_cast(int, x), 0x121, 0xF, 0xF, true)); }
; __device__ __forceinline__ float dpp_ror15(float x) { return __builtin_bit_cast(float, __builtin_amdgcn_mov_dpp(__builtin_bit_cast(int, x), 0x12F, 0xF, 0xF, true)); }
;     __device__ __forceinline__ void operator()(const f32x4 (&acc)[2][2][4][2], const Unit& u, int wr, int wc, int fr, int fq) const {
;     ...
;                         for (int m = 0; m < 4; ++m) { uv[m] = uv[m] * rs[m]; rv[m] = (f32x2){dpp_ror1(uv[m][0]), dpp_ror1(uv[m][1])}; lv[m] = (f32x2){dpp_ror15(uv[m][0]), dpp_ror15(uv[m][1])}; }
; #pragma unroll
;                         for (int m = 0; m < 4; ++m) { const f32x2 pv_ = (m > 0 && f0) ? rv[m > 0 ? m - 1 : 0] : rv[m], nv_ = (m < 3 && f15) ? lv[m < 3 ? m + 1 : 3] : lv[m];
;                             cv[m] = bv + wv0 * pv_ + wv1 * uv[m] + wv2 * nv_; }
;                     }
;                     asm volatile("" : "+v"(cv[0]), "+v"(cv[1]), "+v"(cv[2]), "+v"(cv[3]));
;                     {
;                         f32x2 rg[4], lg[4];
; #pragma unroll
;                         for (int m = 0; m < 4; ++m) { ug[m] = ug[m] * rs[m]; rg[m] = (f32x2){dpp_ror1(ug[m][0]), dpp_ror1(ug[m][1])}; lg[m] = (f32x2){dpp_ror15(ug[m][0]), dpp_ror15(ug[m][1])}; }
; #pragma unroll
;                         for (int m = 0; m < 4; ++m) { const f32x2 pg_ = (m > 0 && f0) ? rg[m > 0 ? m - 1 : 0] : rg[m], ng_ = (m < 3 && f15) ? lg[m < 3 ? m + 1 : 3] : lg[m];
;                             const f32x2 cgt = bg + wg0 * pg_ + wg1 * ug[m] + wg2 * ng_;
;                             const f32x2 e = cgt * (-LOG2E);
;                             const f32x2 d = (f32x2){__builtin_amdgcn_exp2f(e[0]), __builtin_amdgcn_exp2f(e[1])} + 1.f;
;                             const f32x2 sg = {__builtin_amdgcn_rcpf(d[0]), __builtin_amdgcn_rcpf(d[1])};
;                             const f32x2 ov = cv[m] * cgt * sg;
;                             outw[m][n][jp] = cvtpk(ov[0], ov[1]); }
	v_exp_f32_e64 v132, -v124
	v_exp_f32_e64 v133, -v125
	v_pk_mul_f32 v[102:103], v[174:175], v[102:103] op_sel_hi:[0,1]
	v_pk_mul_f32 v[122:123], v[122:123], v[124:125]
	v_cndmask_b32_e64 v111, v109, v111, s[4:5]
	v_cndmask_b32_e64 v110, v105, v110, s[4:5]
	v_pk_add_f32 v[132:133], v[132:133], 1.0 op_sel_hi:[1,0]
	v_mov_b32_dpp v140, v102 row_ror:15 row_mask:0xf bank_mask:0xf bound_ctrl:1
	v_rcp_f32_e32 v132, v132
	v_rcp_f32_e32 v133, v133
	v_mov_b32_dpp v141, v103 row_ror:15 row_mask:0xf bank_mask:0xf bound_ctrl:1
	v_pk_fma_f32 v[110:111], v[116:117], v[110:111], v[130:131]
	v_mov_b32_dpp v138, v102 row_ror:1 row_mask:0xf bank_mask:0xf bound_ctrl:1
	v_pk_mul_f32 v[122:123], v[122:123], v[132:133]
	v_pk_fma_f32 v[106:107], v[128:129], v[106:107], v[110:111]
	v_cvt_pk_bf16_f32 v97, v122, v123
	v_cndmask_b32_e64 v123, v137, v141, s[6:7]
	v_cndmask_b32_e64 v122, v136, v140, s[6:7]
	v_pk_fma_f32 v[106:107], v[112:113], v[122:123], v[106:107]
	v_mov_b32_dpp v139, v103 row_ror:1 row_mask:0xf bank_mask:0xf bound_ctrl:1
	v_exp_f32_e64 v110, -v106
	v_exp_f32_e64 v111, -v107
	v_pk_mul_f32 v[106:107], v[120:121], v[106:107]
	v_pk_mul_f32 v[98:99], v[176:177], v[98:99] op_sel_hi:[0,1]
	v_pk_add_f32 v[110:111], v[110:111], 1.0 op_sel_hi:[1,0]
	s_nop 0
	v_rcp_f32_e32 v110, v110
	v_rcp_f32_e32 v111, v111
	v_mov_b32_dpp v126, v98 row_ror:15 row_mask:0xf bank_mask:0xf bound_ctrl:1
	v_mov_b32_dpp v127, v99 row_ror:15 row_mask:0xf bank_mask:0xf bound_ctrl:1
	v_mov_b32_dpp v142, v98 row_ror:1 row_mask:0xf bank_mask:0xf bound_ctrl:1
	v_pk_mul_f32 v[106:107], v[106:107], v[110:111]
	v_cndmask_b32_e64 v111, v141, v127, s[6:7]
	v_cvt_pk_bf16_f32 v101, v106, v107
	v_cndmask_b32_e64 v107, v139, v109, s[4:5]
	v_cndmask_b32_e64 v106, v138, v105, s[4:5]
	v_pk_fma_f32 v[106:107], v[116:117], v[106:107], v[130:131]
	v_cndmask_b32_e64 v110, v140, v126, s[6:7]
	v_pk_fma_f32 v[102:103], v[128:129], v[102:103], v[106:107]
	v_mov_b32_dpp v143, v99 row_ror:1 row_mask:0xf bank_mask:0xf bound_ctrl:1
	v_pk_fma_f32 v[102:103], v[112:113], v[110:111], v[102:103]
	s_nop 0
	v_exp_f32_e64 v106, -v102
	v_exp_f32_e64 v107, -v103
	v_pk_mul_f32 v[102:103], v[118:119], v[102:103]
	s_nop 0
	v_pk_add_f32 v[106:107], v[106:107], 1.0 op_sel_hi:[1,0]
	s_nop 0
	v_rcp_f32_e32 v106, v106
	v_rcp_f32_e32 v107, v107
	s_nop 0
	v_pk_mul_f32 v[102:103], v[102:103], v[106:107]
	s_nop 0
	v_cvt_pk_bf16_f32 v105, v102, v103
	v_cndmask_b32_e64 v103, v143, v139, s[4:5]
	v_cndmask_b32_e64 v102, v142, v138, s[4:5]
	v_pk_fma_f32 v[102:103], v[116:117], v[102:103], v[130:131]
	s_nop 0
	v_pk_fma_f32 v[98:99], v[128:129], v[98:99], v[102:103]
	s_nop 0
	v_pk_fma_f32 v[98:99], v[112:113], v[126:127], v[98:99]
	s_nop 0
	v_exp_f32_e64 v102, -v98
	v_exp_f32_e64 v103, -v99
	v_pk_mul_f32 v[98:99], v[114:115], v[98:99]
	s_nop 0
	v_pk_add_f32 v[102:103], v[102:103], 1.0 op_sel_hi:[1,0]
	s_nop 0
	v_rcp_f32_e32 v102, v102
	v_rcp_f32_e32 v103, v103
	s_nop 0
	v_pk_mul_f32 v[98:99], v[98:99], v[102:103]
	s_nop 0
	v_cvt_pk_bf16_f32 v109, v98, v99
	global_load_dwordx4 v[114:117], v[170:171], off offset:144
	global_load_dwordx4 v[110:113], v[170:171], off offset:176
	global_load_dwordx4 v[122:125], v[170:171], off offset:128
	global_load_dwordx4 v[126:129], v[170:171], off offset:160
	s_waitcnt vmcnt(3)
	v_mov_b32_e32 v118, v116
	v_pk_mul_f32 v[92:93], v[172:173], v[92:93] op_sel_hi:[0,1]
	v_pk_mul_f32 v[88:89], v[144:145], v[88:89] op_sel_hi:[0,1]
	s_waitcnt vmcnt(1)
	v_mov_b32_e32 v98, v122
	s_waitcnt vmcnt(0)
	v_mov_b32_e32 v99, v126
	v_mov_b32_e32 v103, v128
	v_mov_b32_dpp v106, v92 row_ror:1 row_mask:0xf bank_mask:0xf bound_ctrl:1
	v_mov_b32_dpp v107, v93 row_ror:1 row_mask:0xf bank_mask:0xf bound_ctrl:1
	v_mov_b32_dpp v130, v88 row_ror:1 row_mask:0xf bank_mask:0xf bound_ctrl:1
	v_mov_b32_dpp v131, v89 row_ror:1 row_mask:0xf bank_mask:0xf bound_ctrl:1
	v_mov_b32_e32 v128, v125
	v_mov_b32_e32 v102, v124
	v_pk_mul_f32 v[84:85], v[174:175], v[84:85] op_sel_hi:[0,1]
	v_pk_fma_f32 v[124:125], v[98:99], v[106:107], v[128:129]
	v_cndmask_b32_e64 v107, v131, v107, s[4:5]
	v_cndmask_b32_e64 v106, v130, v106, s[4:5]
	v_mov_b32_e32 v126, v123
	v_mov_b32_dpp v134, v84 row_ror:1 row_mask:0xf bank_mask:0xf bound_ctrl:1
	v_mov_b32_dpp v135, v85 row_ror:1 row_mask:0xf bank_mask:0xf bound_ctrl:1
	v_pk_fma_f32 v[106:107], v[98:99], v[106:107], v[128:129]
	v_mov_b32_dpp v132, v88 row_ror:15 row_mask:0xf bank_mask:0xf bound_ctrl:1
	v_mov_b32_dpp v133, v89 row_ror:15 row_mask:0xf bank_mask:0xf bound_ctrl:1
	v_pk_mul_f32 v[80:81], v[176:177], v[80:81] op_sel_hi:[0,1]
	v_pk_fma_f32 v[88:89], v[126:127], v[88:89], v[106:107]
	v_cndmask_b32_e64 v107, v135, v131, s[4:5]
	v_cndmask_b32_e64 v106, v134, v130, s[4:5]
	v_mov_b32_dpp v138, v80 row_ror:1 row_mask:0xf bank_mask:0xf bound_ctrl:1
	v_mov_b32_dpp v139, v81 row_ror:1 row_mask:0xf bank_mask:0xf bound_ctrl:1
	v_pk_fma_f32 v[106:107], v[98:99], v[106:107], v[128:129]
	v_mov_b32_e32 v119, v112
	v_mov_b32_dpp v112, v92 row_ror:15 row_mask:0xf bank_mask:0xf bound_ctrl:1
	v_mov_b32_dpp v116, v93 row_ror:15 row_mask:0xf bank_mask:0xf bound_ctrl:1
	v_mov_b32_dpp v136, v84 row_ror:15 row_mask:0xf bank_mask:0xf bound_ctrl:1
	v_mov_b32_dpp v137, v85 row_ror:15 row_mask:0xf bank_mask:0xf bound_ctrl:1
	v_pk_fma_f32 v[84:85], v[126:127], v[84:85], v[106:107]
	v_cndmask_b32_e64 v107, v139, v135, s[4:5]
	v_cndmask_b32_e64 v106, v138, v134, s[4:5]
	v_cndmask_b32_e64 v123, v116, v133, s[6:7]
	v_cndmask_b32_e64 v122, v112, v132, s[6:7]
	v_pk_fma_f32 v[92:93], v[126:127], v[92:93], v[124:125]
	v_pk_fma_f32 v[98:99], v[98:99], v[106:107], v[128:129]
	v_mov_b32_e32 v120, v114
	v_mov_b32_e32 v121, v110
	v_mov_b32_e32 v110, v115
; __device__ __forceinline__ unsigned cvtpk(float lo, float hi) { f32x2 v = {lo, hi}; bf16x2_t b = __builtin_convertvector(v, bf16x2_t); return __builtin_bit_cast(unsigned, b); }
; __device__ __forceinline__ float dpp_ror1(float x) { return __builtin_bit_cast(float, __builtin_amdgcn_mov_dpp(__builtin_bit_cast(int, x), 0x121, 0xF, 0xF, true)); }
; __device__ __forceinline__ float dpp_ror15(float x) { return __builtin_bit_cast(float, __builtin_amdgcn_mov_dpp(__builtin_bit_cast(int, x), 0x12F, 0xF, 0xF, true)); }
;     __device__ __forceinline__ void operator()(const f32x4 (&acc)[2][2][4][2], const Unit& u, int wr, int wc, int fr, int fq) const {
;     ...
;                         for (int m = 0; m < 4; ++m) { uv[m] = uv[m] * rs[m]; rv[m] = (f32x2){dpp_ror1(uv[m][0]), dpp_ror1(uv[m][1])}; lv[m] = (f32x2){dpp_ror15(uv[m][0]), dpp_ror15(uv[m][1])}; }
; #pragma unroll
;                         for (int m = 0; m < 4; ++m) { const f32x2 pv_ = (m > 0 && f0) ? rv[m > 0 ? m - 1 : 0] : rv[m], nv_ = (m < 3 && f15) ? lv[m < 3 ? m + 1 : 3] : lv[m];
;                             cv[m] = bv + wv0 * pv_ + wv1 * uv[m] + wv2 * nv_; }
;                     }
;                     asm volatile("" : "+v"(cv[0]), "+v"(cv[1]), "+v"(cv[2]), "+v"(cv[3]));
;                     {
;                         f32x2 rg[4], lg[4];
; #pragma unroll
;                         for (int m = 0; m < 4; ++m) { ug[m] = ug[m] * rs[m]; rg[m] = (f32x2){dpp_ror1(ug[m][0]), dpp_ror1(ug[m][1])}; lg[m] = (f32x2){dpp_ror15(ug[m][0]), dpp_ror15(ug[m][1])}; }
; #pragma unroll
;                         for (int m = 0; m < 4; ++m) { const f32x2 pg_ = (m > 0 && f0) ? rg[m > 0 ? m - 1 : 0] : rg[m], ng_ = (m < 3 && f15) ? lg[m < 3 ? m + 1 : 3] : lg[m];
;                             const f32x2 cgt = bg + wg0 * pg_ + wg1 * ug[m] + wg2 * ng_;
;                             const f32x2 e = cgt * (-LOG2E);
;                             const f32x2 d = (f32x2){__builtin_amdgcn_exp2f(e[0]), __builtin_amdgcn_exp2f(e[1])} + 1.f;
;                             const f32x2 sg = {__builtin_amdgcn_rcpf(d[0]), __builtin_amdgcn_rcpf(d[1])};
;                             const f32x2 ov = cv[m] * cgt * sg;
;                             outw[m][n][jp] = cvtpk(ov[0], ov[1]); }
	v_mov_b32_dpp v114, v80 row_ror:15 row_mask:0xf bank_mask:0xf bound_ctrl:1
	v_mov_b32_dpp v115, v81 row_ror:15 row_mask:0xf bank_mask:0xf bound_ctrl:1
	v_pk_fma_f32 v[92:93], v[102:103], v[122:123], v[92:93]
	v_cndmask_b32_e64 v123, v133, v137, s[6:7]
	v_cndmask_b32_e64 v122, v132, v136, s[6:7]
	v_pk_fma_f32 v[80:81], v[126:127], v[80:81], v[98:99]
	v_pk_mul_f32 v[98:99], v[172:173], v[76:77] op_sel_hi:[0,1]
	v_pk_fma_f32 v[88:89], v[102:103], v[122:123], v[88:89]
	v_cndmask_b32_e64 v123, v137, v115, s[6:7]
	v_cndmask_b32_e64 v122, v136, v114, s[6:7]
	v_mov_b32_dpp v76, v98 row_ror:1 row_mask:0xf bank_mask:0xf bound_ctrl:1
	v_mov_b32_dpp v77, v99 row_ror:1 row_mask:0xf bank_mask:0xf bound_ctrl:1
	v_pk_mul_f32 v[72:73], v[144:145], v[72:73] op_sel_hi:[0,1]
	v_mov_b32_e32 v112, v117
	v_pk_fma_f32 v[84:85], v[102:103], v[122:123], v[84:85]
	v_pk_fma_f32 v[80:81], v[102:103], v[114:115], v[80:81]
	v_mov_b32_dpp v102, v98 row_ror:15 row_mask:0xf bank_mask:0xf bound_ctrl:1
	v_mov_b32_dpp v103, v99 row_ror:15 row_mask:0xf bank_mask:0xf bound_ctrl:1
	v_mov_b32_dpp v123, v72 row_ror:15 row_mask:0xf bank_mask:0xf bound_ctrl:1
	v_mov_b32_dpp v124, v73 row_ror:15 row_mask:0xf bank_mask:0xf bound_ctrl:1
	v_pk_fma_f32 v[106:107], v[120:121], v[76:77], v[112:113]
	v_cndmask_b32_e64 v103, v103, v124, s[6:7]
	v_cndmask_b32_e64 v102, v102, v123, s[6:7]
	v_pk_fma_f32 v[98:99], v[110:111], v[98:99], v[106:107]
	v_mov_b32_dpp v116, v72 row_ror:1 row_mask:0xf bank_mask:0xf bound_ctrl:1
	v_pk_fma_f32 v[98:99], v[118:119], v[102:103], v[98:99]
	v_mov_b32_dpp v122, v73 row_ror:1 row_mask:0xf bank_mask:0xf bound_ctrl:1
	v_exp_f32_e64 v102, -v98
	v_exp_f32_e64 v103, -v99
	v_pk_mul_f32 v[68:69], v[174:175], v[68:69] op_sel_hi:[0,1]
	v_pk_mul_f32 v[92:93], v[92:93], v[98:99]
	v_cndmask_b32_e64 v77, v122, v77, s[4:5]
	v_cndmask_b32_e64 v76, v116, v76, s[4:5]
	v_pk_add_f32 v[102:103], v[102:103], 1.0 op_sel_hi:[1,0]
	v_mov_b32_dpp v127, v68 row_ror:15 row_mask:0xf bank_mask:0xf bound_ctrl:1
	v_rcp_f32_e32 v102, v102
	v_rcp_f32_e32 v103, v103
	v_mov_b32_dpp v128, v69 row_ror:15 row_mask:0xf bank_mask:0xf bound_ctrl:1
	v_pk_fma_f32 v[76:77], v[120:121], v[76:77], v[112:113]
	v_mov_b32_dpp v125, v68 row_ror:1 row_mask:0xf bank_mask:0xf bound_ctrl:1
	v_pk_mul_f32 v[92:93], v[92:93], v[102:103]
	v_pk_fma_f32 v[72:73], v[110:111], v[72:73], v[76:77]
	v_cvt_pk_bf16_f32 v98, v92, v93
	v_cndmask_b32_e64 v93, v124, v128, s[6:7]
	v_cndmask_b32_e64 v92, v123, v127, s[6:7]
	v_pk_fma_f32 v[72:73], v[118:119], v[92:93], v[72:73]
	v_mov_b32_dpp v126, v69 row_ror:1 row_mask:0xf bank_mask:0xf bound_ctrl:1
	v_exp_f32_e64 v76, -v72
	v_exp_f32_e64 v77, -v73
	v_pk_mul_f32 v[72:73], v[88:89], v[72:73]
	v_pk_mul_f32 v[64:65], v[176:177], v[64:65] op_sel_hi:[0,1]
	v_pk_add_f32 v[76:77], v[76:77], 1.0 op_sel_hi:[1,0]
	s_nop 0
	v_rcp_f32_e32 v76, v76
	v_rcp_f32_e32 v77, v77
	v_mov_b32_dpp v114, v64 row_ror:15 row_mask:0xf bank_mask:0xf bound_ctrl:1
	v_mov_b32_dpp v115, v65 row_ror:15 row_mask:0xf bank_mask:0xf bound_ctrl:1
	v_mov_b32_dpp v129, v64 row_ror:1 row_mask:0xf bank_mask:0xf bound_ctrl:1
	v_pk_mul_f32 v[72:73], v[72:73], v[76:77]
	v_cndmask_b32_e64 v77, v128, v115, s[6:7]
	v_cvt_pk_bf16_f32 v102, v72, v73
	v_cndmask_b32_e64 v73, v126, v122, s[4:5]
	v_cndmask_b32_e64 v72, v125, v116, s[4:5]
	v_pk_fma_f32 v[72:73], v[120:121], v[72:73], v[112:113]
	v_cndmask_b32_e64 v76, v127, v114, s[6:7]
	v_pk_fma_f32 v[68:69], v[110:111], v[68:69], v[72:73]
	v_mov_b32_dpp v130, v65 row_ror:1 row_mask:0xf bank_mask:0xf bound_ctrl:1
	v_pk_fma_f32 v[68:69], v[118:119], v[76:77], v[68:69]
	s_nop 0
	v_exp_f32_e64 v72, -v68
	v_exp_f32_e64 v73, -v69
	v_pk_mul_f32 v[68:69], v[84:85], v[68:69]
	s_nop 0
	v_pk_add_f32 v[72:73], v[72:73], 1.0 op_sel_hi:[1,0]
	s_nop 0
	v_rcp_f32_e32 v72, v72
	v_rcp_f32_e32 v73, v73
	s_nop 0
	v_pk_mul_f32 v[68:69], v[68:69], v[72:73]
	s_nop 0
	v_cvt_pk_bf16_f32 v106, v68, v69
	v_cndmask_b32_e64 v69, v130, v126, s[4:5]
	v_cndmask_b32_e64 v68, v129, v125, s[4:5]
	v_pk_fma_f32 v[68:69], v[120:121], v[68:69], v[112:113]
	s_nop 0
	v_pk_fma_f32 v[64:65], v[110:111], v[64:65], v[68:69]
	s_nop 0
	v_pk_fma_f32 v[64:65], v[118:119], v[114:115], v[64:65]
	s_nop 0
	v_exp_f32_e64 v68, -v64
	v_exp_f32_e64 v69, -v65
	v_pk_mul_f32 v[64:65], v[80:81], v[64:65]
	s_nop 0
	v_pk_add_f32 v[68:69], v[68:69], 1.0 op_sel_hi:[1,0]
	s_nop 0
	v_rcp_f32_e32 v68, v68
	v_rcp_f32_e32 v69, v69
	s_nop 0
	v_pk_mul_f32 v[64:65], v[64:65], v[68:69]
	s_nop 0
	v_cvt_pk_bf16_f32 v110, v64, v65
	global_load_dwordx4 v[116:119], v[170:171], off offset:192
	global_load_dwordx4 v[120:123], v[170:171], off offset:224
	global_load_dwordx4 v[124:127], v[170:171], off offset:208
	global_load_dwordx4 v[112:115], v[170:171], off offset:240
	s_waitcnt vmcnt(3)
	v_mov_b32_e32 v134, v118
	v_pk_mul_f32 v[78:79], v[172:173], v[78:79] op_sel_hi:[0,1]
	v_pk_mul_f32 v[74:75], v[144:145], v[74:75] op_sel_hi:[0,1]
	s_waitcnt vmcnt(1)
	v_mov_b32_e32 v136, v124
	v_mov_b32_dpp v84, v78 row_ror:1 row_mask:0xf bank_mask:0xf bound_ctrl:1
	v_mov_b32_dpp v85, v79 row_ror:1 row_mask:0xf bank_mask:0xf bound_ctrl:1
	s_waitcnt vmcnt(0)
;     __device__ __forceinline__ void operator()(const f32x4 (&acc)[2][2][4][2], const Unit& u, int wr, int wc, int fr, int fq) const {
;     ...
;                         for (int m = 0; m < 4; ++m) { uv[m] = uv[m] * rs[m]; rv[m] = (f32x2){dpp_ror1(uv[m][0]), dpp_ror1(uv[m][1])}; lv[m] = (f32x2){dpp_ror15(uv[m][0]), dpp_ror15(uv[m][1])}; }
; #pragma unroll
;                         for (int m = 0; m < 4; ++m) { const f32x2 pv_ = (m > 0 && f0) ? rv[m > 0 ? m - 1 : 0] : rv[m], nv_ = (m < 3 && f15) ? lv[m < 3 ? m + 1 : 3] : lv[m];
;                             cv[m] = bv + wv0 * pv_ + wv1 * uv[m] + wv2 * nv_; }
;                     }
;                     asm volatile("" : "+v"(cv[0]), "+v"(cv[1]), "+v"(cv[2]), "+v"(cv[3]));
;                     {
;                         f32x2 rg[4], lg[4];
; #pragma unroll
;                         for (int m = 0; m < 4; ++m) { ug[m] = ug[m] * rs[m]; rg[m] = (f32x2){dpp_ror1(ug[m][0]), dpp_ror1(ug[m][1])}; lg[m] = (f32x2){dpp_ror15(ug[m][0]), dpp_ror15(ug[m][1])}; }
; #pragma unroll
;                         for (int m = 0; m < 4; ++m) { const f32x2 pg_ = (m > 0 && f0) ? rg[m > 0 ? m - 1 : 0] : rg[m], ng_ = (m < 3 && f15) ? lg[m < 3 ? m + 1 : 3] : lg[m];
;                             const f32x2 cgt = bg + wg0 * pg_ + wg1 * ug[m] + wg2 * ng_;
;                             const f32x2 e = cgt * (-LOG2E);
;                             const f32x2 d = (f32x2){__builtin_amdgcn_exp2f(e[0]), __builtin_amdgcn_exp2f(e[1])} + 1.f;
;                             const f32x2 sg = {__builtin_amdgcn_rcpf(d[0]), __builtin_amdgcn_rcpf(d[1])};
;                             const f32x2 ov = cv[m] * cgt * sg;
;                             outw[m][n][jp] = cvtpk(ov[0], ov[1]); }
;                     }
;                     asm volatile("" : "+v"(outw[0][n][jp]), "+v"(outw[1][n][jp]), "+v"(outw[2][n][jp]), "+v"(outw[3][n][jp]) :: "memory"); __builtin_amdgcn_sched_barrier(0);
;                 }
; #pragma unroll
;             for (int m = 0; m < 4; ++m) { const int i = 16 * m + fr, t = tbase + i;
;                 if (i >= 1 && i <= 62 && t < slen) { u32x4 w; w.x = outw[m][0][0]; w.y = outw[m][0][1]; w.z = outw[m][1][0]; w.w = outw[m][1][1];
;                     *(u32x4*)(Gout + (size_t)(seqbase + t) * DFF + 128 * u.pn + 32 * wc + 8 * fq) = w; } }
	v_mov_b32_e32 v137, v112
	v_mov_b32_e32 v139, v114
	v_mov_b32_e32 v114, v127
	v_pk_mul_f32 v[64:65], v[172:173], v[94:95] op_sel_hi:[0,1]
	v_pk_mul_f32 v[68:69], v[144:145], v[90:91] op_sel_hi:[0,1]
	v_mov_b32_dpp v130, v78 row_ror:15 row_mask:0xf bank_mask:0xf bound_ctrl:1
	v_mov_b32_dpp v131, v79 row_ror:15 row_mask:0xf bank_mask:0xf bound_ctrl:1
	v_mov_b32_dpp v142, v74 row_ror:15 row_mask:0xf bank_mask:0xf bound_ctrl:1
	v_mov_b32_dpp v143, v75 row_ror:15 row_mask:0xf bank_mask:0xf bound_ctrl:1
	v_mov_b32_e32 v135, v122
	v_mov_b32_e32 v112, v125
	v_mov_b32_e32 v122, v119
	v_pk_fma_f32 v[118:119], v[136:137], v[84:85], v[114:115]
	v_mov_b32_dpp v80, v64 row_ror:1 row_mask:0xf bank_mask:0xf bound_ctrl:1
	v_mov_b32_dpp v81, v65 row_ror:1 row_mask:0xf bank_mask:0xf bound_ctrl:1
	v_mov_b32_dpp v92, v68 row_ror:1 row_mask:0xf bank_mask:0xf bound_ctrl:1
	v_mov_b32_dpp v93, v69 row_ror:1 row_mask:0xf bank_mask:0xf bound_ctrl:1
	v_cndmask_b32_e64 v131, v131, v143, s[6:7]
	v_cndmask_b32_e64 v130, v130, v142, s[6:7]
	v_mov_b32_e32 v132, v116
	v_mov_b32_e32 v133, v120
	v_mov_b32_e32 v138, v126
	v_pk_fma_f32 v[78:79], v[112:113], v[78:79], v[118:119]
	v_cndmask_b32_e64 v89, v93, v81, s[4:5]
	v_cndmask_b32_e64 v88, v92, v80, s[4:5]
	v_mov_b32_e32 v120, v117
	v_pk_fma_f32 v[80:81], v[132:133], v[80:81], v[122:123]
	v_pk_fma_f32 v[78:79], v[138:139], v[130:131], v[78:79]
	v_pk_mul_f32 v[72:73], v[174:175], v[86:87] op_sel_hi:[0,1]
	v_mov_b32_dpp v86, v64 row_ror:15 row_mask:0xf bank_mask:0xf bound_ctrl:1
	v_mov_b32_dpp v87, v65 row_ror:15 row_mask:0xf bank_mask:0xf bound_ctrl:1
	v_pk_fma_f32 v[64:65], v[120:121], v[64:65], v[80:81]
	v_exp_f32_e64 v80, -v78
	v_exp_f32_e64 v81, -v79
	v_mov_b32_dpp v140, v74 row_ror:1 row_mask:0xf bank_mask:0xf bound_ctrl:1
	v_mov_b32_dpp v141, v75 row_ror:1 row_mask:0xf bank_mask:0xf bound_ctrl:1
	v_pk_mul_f32 v[76:77], v[176:177], v[82:83] op_sel_hi:[0,1]
	v_pk_mul_f32 v[70:71], v[174:175], v[70:71] op_sel_hi:[0,1]
	v_mov_b32_dpp v90, v68 row_ror:15 row_mask:0xf bank_mask:0xf bound_ctrl:1
	v_mov_b32_dpp v91, v69 row_ror:15 row_mask:0xf bank_mask:0xf bound_ctrl:1
	v_cndmask_b32_e64 v85, v141, v85, s[4:5]
	v_cndmask_b32_e64 v84, v140, v84, s[4:5]
	v_pk_mul_f32 v[66:67], v[176:177], v[66:67] op_sel_hi:[0,1]
	v_mov_b32_dpp v99, v72 row_ror:1 row_mask:0xf bank_mask:0xf bound_ctrl:1
	v_mov_b32_dpp v103, v73 row_ror:1 row_mask:0xf bank_mask:0xf bound_ctrl:1
	v_mov_b32_dpp v107, v76 row_ror:1 row_mask:0xf bank_mask:0xf bound_ctrl:1
	v_mov_b32_dpp v111, v77 row_ror:1 row_mask:0xf bank_mask:0xf bound_ctrl:1
	v_mov_b32_dpp v174, v70 row_ror:15 row_mask:0xf bank_mask:0xf bound_ctrl:1
	v_mov_b32_dpp v176, v71 row_ror:15 row_mask:0xf bank_mask:0xf bound_ctrl:1
	v_cndmask_b32_e64 v87, v87, v91, s[6:7]
	v_cndmask_b32_e64 v86, v86, v90, s[6:7]
	v_pk_fma_f32 v[84:85], v[136:137], v[84:85], v[114:115]
	v_cndmask_b32_e64 v93, v103, v93, s[4:5]
	v_cndmask_b32_e64 v92, v99, v92, s[4:5]
	v_cndmask_b32_e64 v129, v111, v103, s[4:5]
	v_cndmask_b32_e64 v128, v107, v99, s[4:5]
	v_pk_fma_f32 v[64:65], v[134:135], v[86:87], v[64:65]
	v_cndmask_b32_e64 v87, v143, v176, s[6:7]
	v_cndmask_b32_e64 v86, v142, v174, s[6:7]
	v_pk_fma_f32 v[74:75], v[112:113], v[74:75], v[84:85]
	v_mov_b32_dpp v94, v72 row_ror:15 row_mask:0xf bank_mask:0xf bound_ctrl:1
	v_mov_b32_dpp v95, v73 row_ror:15 row_mask:0xf bank_mask:0xf bound_ctrl:1
	v_mov_b32_dpp v82, v76 row_ror:15 row_mask:0xf bank_mask:0xf bound_ctrl:1
	v_mov_b32_dpp v83, v77 row_ror:15 row_mask:0xf bank_mask:0xf bound_ctrl:1
	v_pk_fma_f32 v[88:89], v[132:133], v[88:89], v[122:123]
	v_pk_fma_f32 v[92:93], v[132:133], v[92:93], v[122:123]
	v_pk_fma_f32 v[116:117], v[132:133], v[128:129], v[122:123]
	v_pk_add_f32 v[80:81], v[80:81], 1.0 op_sel_hi:[1,0]
	v_pk_fma_f32 v[74:75], v[138:139], v[86:87], v[74:75]
	v_cndmask_b32_e64 v91, v91, v95, s[6:7]
	v_cndmask_b32_e64 v90, v90, v94, s[6:7]
	v_cndmask_b32_e64 v95, v95, v83, s[6:7]
	v_cndmask_b32_e64 v94, v94, v82, s[6:7]
	v_pk_fma_f32 v[68:69], v[120:121], v[68:69], v[88:89]
	v_pk_fma_f32 v[72:73], v[120:121], v[72:73], v[92:93]
	v_pk_fma_f32 v[76:77], v[120:121], v[76:77], v[116:117]
	v_rcp_f32_e32 v80, v80
	v_rcp_f32_e32 v81, v81
	v_exp_f32_e64 v84, -v74
	v_exp_f32_e64 v85, -v75
	v_pk_fma_f32 v[68:69], v[134:135], v[90:91], v[68:69]
	v_pk_fma_f32 v[72:73], v[134:135], v[94:95], v[72:73]
	v_pk_fma_f32 v[76:77], v[134:135], v[82:83], v[76:77]
	v_mov_b32_dpp v144, v70 row_ror:1 row_mask:0xf bank_mask:0xf bound_ctrl:1
	v_pk_mul_f32 v[64:65], v[64:65], v[78:79]
	v_mov_b32_dpp v172, v71 row_ror:1 row_mask:0xf bank_mask:0xf bound_ctrl:1
	v_pk_mul_f32 v[64:65], v[64:65], v[80:81]
	v_cndmask_b32_e64 v79, v172, v141, s[4:5]
	v_cvt_pk_bf16_f32 v99, v64, v65
	v_pk_add_f32 v[64:65], v[84:85], 1.0 op_sel_hi:[1,0]
	v_cndmask_b32_e64 v78, v144, v140, s[4:5]
	v_rcp_f32_e32 v64, v64
	v_rcp_f32_e32 v65, v65
	v_mov_b32_dpp v178, v66 row_ror:1 row_mask:0xf bank_mask:0xf bound_ctrl:1
	v_mov_b32_dpp v88, v67 row_ror:1 row_mask:0xf bank_mask:0xf bound_ctrl:1
	v_mov_b32_dpp v82, v66 row_ror:15 row_mask:0xf bank_mask:0xf bound_ctrl:1
	v_mov_b32_dpp v83, v67 row_ror:15 row_mask:0xf bank_mask:0xf bound_ctrl:1
	v_pk_fma_f32 v[78:79], v[136:137], v[78:79], v[114:115]
	v_pk_mul_f32 v[68:69], v[68:69], v[74:75]
	v_cndmask_b32_e64 v81, v176, v83, s[6:7]
	v_cndmask_b32_e64 v80, v174, v82, s[6:7]
	v_pk_fma_f32 v[70:71], v[112:113], v[70:71], v[78:79]
	v_pk_mul_f32 v[64:65], v[68:69], v[64:65]
	v_cndmask_b32_e64 v69, v88, v172, s[4:5]
	v_cndmask_b32_e64 v68, v178, v144, s[4:5]
	v_pk_fma_f32 v[70:71], v[138:139], v[80:81], v[70:71]
	v_pk_fma_f32 v[68:69], v[136:137], v[68:69], v[114:115]
	v_exp_f32_e64 v78, -v70
	v_exp_f32_e64 v79, -v71
	v_pk_fma_f32 v[66:67], v[112:113], v[66:67], v[68:69]
	v_pk_fma_f32 v[66:67], v[138:139], v[82:83], v[66:67]
	v_cvt_pk_bf16_f32 v103, v64, v65
	v_exp_f32_e64 v68, -v66
	v_exp_f32_e64 v69, -v67
	v_pk_add_f32 v[64:65], v[78:79], 1.0 op_sel_hi:[1,0]
	v_rcp_f32_e32 v64, v64
	v_rcp_f32_e32 v65, v65
	v_pk_mul_f32 v[70:71], v[72:73], v[70:71]
	v_pk_add_f32 v[68:69], v[68:69], 1.0 op_sel_hi:[1,0]
	v_pk_mul_f32 v[64:65], v[70:71], v[64:65]
	v_rcp_f32_e32 v68, v68
	v_rcp_f32_e32 v69, v69
	v_cvt_pk_bf16_f32 v107, v64, v65
	v_pk_mul_f32 v[64:65], v[76:77], v[66:67]
	s_nop 0
	v_pk_mul_f32 v[64:65], v[64:65], v[68:69]
	s_nop 0
	v_cvt_pk_bf16_f32 v111, v64, v65
	v_cmp_gt_i32_e32 vcc, s51, v190
	s_and_b64 s[14:15], s[8:9], vcc
	v_lshlrev_b32_e32 v144, 1, v160
	s_and_saveexec_b64 s[2:3], s[14:15]
	s_cbranch_execz .LBB0_796
	v_add_u32_e32 v66, s29, v190
	v_mov_b64_e32 v[64:65], s[24:25]
	v_mad_i64_i32 v[64:65], s[14:15], v66, s73, v[64:65]
	v_lshl_add_u64 v[64:65], s[36:37], 1, v[64:65]
	s_lshl_b32 s84, s45, 1
	v_lshl_add_u64 v[64:65], v[64:65], 0, s[84:85]
	v_lshl_add_u64 v[64:65], v[64:65], 0, v[144:145]
	global_store_dwordx4 v[64:65], v[96:99], off

;     __device__ __forceinline__ void operator()(const f32x4 (&acc)[2][2][4][2], const Unit& u, int wr, int wc, int fr, int fq) const {
;     ...
;             const int tbase = t0 + 62 * (2 * ai + wr) - 1;
;             float rs[4];
; #pragma unroll
;             for (int m = 0; m < 4; ++m) { const int t = tbase + 16 * m + fr; const bool vin = (t >= 0) && (t < slen); const int grow = seqbase + (vin ? t : 0);
;                 const f32x4 p = *(const f32x4*)(PS + (size_t)grow * 16 + 4 * fq); float s = (p[0] + p[1]) + (p[2] + p[3]); s = bfly_add<16>(s); s = bfly_add<32>(s); rs[m] = vin ? rsqrtf(s * (1.f / DM) + EPS) : 0.f; }
;             unsigned outw[4][2][2];
; #pragma unroll
;             for (int n = 0; n < 2; ++n)
; #pragma unroll
;                 for (int jp = 0; jp < 2; ++jp) {
;                     const int cidx = (4 * n + 2 * jp) * 2;
;                     const f32x4 c0a = ct[cidx], c0b = ct[cidx + 1], c1a = ct[cidx + 2], c1b = ct[cidx + 3];
.LBB0_802:
	s_or_b64 exec, exec, s[2:3]
	s_addk_i32 s52, 0x7c
	v_add_u32_e32 v81, s52, v161
	v_cmp_gt_u32_e32 vcc, s51, v81
	s_nop 1
	v_cndmask_b32_e32 v64, 0, v81, vcc
	v_add_u32_e32 v64, s29, v64
	v_ashrrev_i32_e32 v65, 31, v64
	v_lshlrev_b64 v[64:65], 6, v[64:65]
	v_lshl_add_u64 v[64:65], v[164:165], 0, v[64:65]
	global_load_dwordx4 v[64:67], v[64:65], off
	s_waitcnt vmcnt(0)
	v_mov_b32_e32 v68, v65
	v_mov_b32_e32 v69, v66
	v_mov_b32_e32 v65, v67
	v_pk_add_f32 v[64:65], v[68:69], v[64:65]
	s_nop 0
	v_add_f32_e32 v64, v64, v65
	v_mov_b32_e32 v65, v64
	s_nop 1
	v_permlane16_swap_b32_e32 v64, v65
	s_waitcnt lgkmcnt(0)
	v_add_f32_e32 v69, v64, v65
	v_add_u32_e32 v64, 16, v81
	v_cmp_gt_u32_e64 s[14:15], s51, v64
	v_mov_b32_e32 v71, v69
	s_nop 1
	v_permlane32_swap_b32_e32 v69, v71
	v_cndmask_b32_e64 v64, 0, v64, s[14:15]
	v_add_u32_e32 v64, s29, v64
	v_ashrrev_i32_e32 v65, 31, v64
	v_lshlrev_b64 v[64:65], 6, v[64:65]
	v_lshl_add_u64 v[64:65], v[164:165], 0, v[64:65]
	global_load_dwordx4 v[64:67], v[64:65], off
	s_waitcnt vmcnt(0)
	v_mov_b32_e32 v72, v65
	v_mov_b32_e32 v73, v66
	v_mov_b32_e32 v65, v67
	v_pk_add_f32 v[64:65], v[72:73], v[64:65]
	s_nop 0
	v_add_f32_e32 v64, v64, v65
	v_mov_b32_e32 v65, v64
	s_nop 1
	v_permlane16_swap_b32_e32 v64, v65
	s_waitcnt lgkmcnt(0)
	v_add_f32_e32 v68, v64, v65
	v_mov_b32_e32 v70, v68
	s_nop 1
	v_permlane32_swap_b32_e32 v68, v70
	v_pk_add_f32 v[64:65], v[68:69], v[70:71]
	v_mov_b64_e32 v[68:69], s[78:79]
	v_pk_fma_f32 v[64:65], v[64:65], s[82:83], v[68:69] op_sel_hi:[1,0,0]
	s_nop 0
	v_mul_f32_e32 v66, 0x4b800000, v65
	v_cmp_gt_f32_e64 s[20:21], s62, v65
	v_cmp_gt_f32_e64 s[18:19], s62, v64
	s_nop 0
	v_cndmask_b32_e64 v65, v65, v66, s[20:21]
	v_rsq_f32_e32 v65, v65
	s_nop 0
	v_mul_f32_e32 v66, 0x45800000, v65
	v_cndmask_b32_e64 v65, v65, v66, s[20:21]
	v_cndmask_b32_e32 v82, 0, v65, vcc
	v_mul_f32_e32 v65, 0x4b800000, v64
	v_cndmask_b32_e64 v64, v64, v65, s[18:19]
	v_rsq_f32_e32 v64, v64
	s_nop 0
	v_mul_f32_e32 v65, 0x45800000, v64
	v_cndmask_b32_e64 v64, v64, v65, s[18:19]
	v_cndmask_b32_e64 v80, 0, v64, s[14:15]
	v_add_u32_e32 v64, 32, v81
	v_cmp_gt_u32_e32 vcc, s51, v64
	s_nop 1
	v_cndmask_b32_e32 v64, 0, v64, vcc
	v_add_u32_e32 v64, s29, v64
	v_ashrrev_i32_e32 v65, 31, v64
	v_lshlrev_b64 v[64:65], 6, v[64:65]
	v_lshl_add_u64 v[64:65], v[164:165], 0, v[64:65]
	global_load_dwordx4 v[64:67], v[64:65], off
	s_waitcnt vmcnt(0)
	v_mov_b32_e32 v70, v65
	v_mov_b32_e32 v71, v66
	v_mov_b32_e32 v65, v67
	v_pk_add_f32 v[64:65], v[70:71], v[64:65]
	s_nop 0
	v_add_f32_e32 v64, v64, v65
	v_mov_b32_e32 v65, v64
	s_nop 1
	v_permlane16_swap_b32_e32 v64, v65
	s_waitcnt lgkmcnt(0)
	v_add_f32_e32 v71, v64, v65
	v_add_u32_e32 v64, 48, v81
	v_cmp_gt_u32_e64 s[14:15], s51, v64
	v_mov_b32_e32 v73, v71
	s_nop 1
	v_permlane32_swap_b32_e32 v71, v73
	v_cndmask_b32_e64 v64, 0, v64, s[14:15]
	v_add_u32_e32 v64, s29, v64
	v_ashrrev_i32_e32 v65, 31, v64
	v_lshlrev_b64 v[64:65], 6, v[64:65]
	v_lshl_add_u64 v[64:65], v[164:165], 0, v[64:65]
	global_load_dwordx4 v[64:67], v[64:65], off
	s_waitcnt vmcnt(0)
	v_mov_b32_e32 v74, v65
	v_mov_b32_e32 v75, v66
	v_mov_b32_e32 v65, v67
	v_pk_add_f32 v[64:65], v[74:75], v[64:65]
	s_nop 0
	v_add_f32_e32 v64, v64, v65
	v_mov_b32_e32 v65, v64
	s_nop 1
	v_permlane16_swap_b32_e32 v64, v65
	s_waitcnt lgkmcnt(0)
	v_add_f32_e32 v70, v64, v65
	v_mov_b32_e32 v72, v70
	s_nop 1
	v_permlane32_swap_b32_e32 v70, v72
	v_pk_add_f32 v[64:65], v[70:71], v[72:73]
	s_nop 0
	v_pk_fma_f32 v[64:65], v[64:65], s[82:83], v[68:69] op_sel_hi:[1,0,0]
	s_nop 0
	v_mul_f32_e32 v66, 0x4b800000, v65
	v_cmp_gt_f32_e64 s[20:21], s62, v65
	v_cmp_gt_f32_e64 s[18:19], s62, v64
	s_nop 0
	v_cndmask_b32_e64 v65, v65, v66, s[20:21]
	v_rsq_f32_e32 v65, v65
	s_nop 0
	v_mul_f32_e32 v66, 0x45800000, v65
	v_cndmask_b32_e64 v65, v65, v66, s[20:21]
	v_cndmask_b32_e32 v84, 0, v65, vcc
	v_mul_f32_e32 v65, 0x4b800000, v64
	v_cndmask_b32_e64 v64, v64, v65, s[18:19]
	v_rsq_f32_e32 v64, v64
	s_nop 0
	v_mul_f32_e32 v65, 0x45800000, v64
	v_cndmask_b32_e64 v64, v64, v65, s[18:19]
	v_cndmask_b32_e64 v86, 0, v64, s[14:15]
	global_load_dwordx4 v[68:71], v[170:171], off offset:16
	global_load_dwordx4 v[64:67], v[170:171], off offset:48
	global_load_dwordx4 v[76:79], v[170:171], off
	global_load_dwordx4 v[72:75], v[170:171], off offset:32
	s_waitcnt vmcnt(3)
	v_mov_b32_e32 v88, v68
	v_pk_mul_f32 v[60:61], v[82:83], v[60:61] op_sel_hi:[0,1]
	v_pk_mul_f32 v[56:57], v[56:57], v[80:81] op_sel_hi:[1,0]
	s_waitcnt vmcnt(1)
	v_mov_b32_e32 v92, v76
	s_waitcnt vmcnt(0)
; __device__ __forceinline__ unsigned cvtpk(float lo, float hi) { f32x2 v = {lo, hi}; bf16x2_t b = __builtin_convertvector(v, bf16x2_t); return __builtin_bit_cast(unsigned, b); }
; __device__ __forceinline__ float dpp_ror1(float x) { return __builtin_bit_cast(float, __builtin_amdgcn_mov_dpp(__builtin_bit_cast(int, x), 0x121, 0xF, 0xF, true)); }
; __device__ __forceinline__ float dpp_ror15(float x) { return __builtin_bit_cast(float, __builtin_amdgcn_mov_dpp(__builtin_bit_cast(int, x), 0x12F, 0xF, 0xF, true)); }
;     __device__ __forceinline__ void operator()(const f32x4 (&acc)[2][2][4][2], const Unit& u, int wr, int wc, int fr, int fq) const {
;     ...
;                         for (int m = 0; m < 4; ++m) { uv[m] = uv[m] * rs[m]; rv[m] = (f32x2){dpp_ror1(uv[m][0]), dpp_ror1(uv[m][1])}; lv[m] = (f32x2){dpp_ror15(uv[m][0]), dpp_ror15(uv[m][1])}; }
; #pragma unroll
;                         for (int m = 0; m < 4; ++m) { const f32x2 pv_ = (m > 0 && f0) ? rv[m > 0 ? m - 1 : 0] : rv[m], nv_ = (m < 3 && f15) ? lv[m < 3 ? m + 1 : 3] : lv[m];
;                             cv[m] = bv + wv0 * pv_ + wv1 * uv[m] + wv2 * nv_; }
;                     }
;                     asm volatile("" : "+v"(cv[0]), "+v"(cv[1]), "+v"(cv[2]), "+v"(cv[3]));
;                     {
;                         f32x2 rg[4], lg[4];
; #pragma unroll
;                         for (int m = 0; m < 4; ++m) { ug[m] = ug[m] * rs[m]; rg[m] = (f32x2){dpp_ror1(ug[m][0]), dpp_ror1(ug[m][1])}; lg[m] = (f32x2){dpp_ror15(ug[m][0]), dpp_ror15(ug[m][1])}; }
; #pragma unroll
;                         for (int m = 0; m < 4; ++m) { const f32x2 pg_ = (m > 0 && f0) ? rg[m > 0 ? m - 1 : 0] : rg[m], ng_ = (m < 3 && f15) ? lg[m < 3 ? m + 1 : 3] : lg[m];
;                             const f32x2 cgt = bg + wg0 * pg_ + wg1 * ug[m] + wg2 * ng_;
;                             const f32x2 e = cgt * (-LOG2E);
;                             const f32x2 d = (f32x2){__builtin_amdgcn_exp2f(e[0]), __builtin_amdgcn_exp2f(e[1])} + 1.f;
;                             const f32x2 sg = {__builtin_amdgcn_rcpf(d[0]), __builtin_amdgcn_rcpf(d[1])};
;                             const f32x2 ov = cv[m] * cgt * sg;
;                             outw[m][n][jp] = cvtpk(ov[0], ov[1]); }
	v_mov_b32_e32 v93, v72
	v_mov_b32_e32 v95, v74
	v_mov_b32_e32 v89, v64
	v_mov_b32_e32 v64, v69
	v_mov_b32_dpp v68, v60 row_ror:1 row_mask:0xf bank_mask:0xf bound_ctrl:1
	v_mov_b32_dpp v69, v61 row_ror:1 row_mask:0xf bank_mask:0xf bound_ctrl:1
	v_mov_b32_dpp v83, v56 row_ror:1 row_mask:0xf bank_mask:0xf bound_ctrl:1
	v_mov_b32_dpp v85, v57 row_ror:1 row_mask:0xf bank_mask:0xf bound_ctrl:1
	v_mov_b32_e32 v74, v79
	v_pk_mul_f32 v[52:53], v[52:53], v[84:85] op_sel_hi:[1,0]
	v_pk_fma_f32 v[96:97], v[92:93], v[68:69], v[74:75]
	v_cndmask_b32_e64 v69, v85, v69, s[4:5]
	v_cndmask_b32_e64 v68, v83, v68, s[4:5]
	v_mov_b32_e32 v72, v77
	v_mov_b32_dpp v87, v56 row_ror:15 row_mask:0xf bank_mask:0xf bound_ctrl:1
	v_mov_b32_dpp v99, v52 row_ror:1 row_mask:0xf bank_mask:0xf bound_ctrl:1
	v_mov_b32_dpp v100, v53 row_ror:1 row_mask:0xf bank_mask:0xf bound_ctrl:1
	v_pk_fma_f32 v[68:69], v[92:93], v[68:69], v[74:75]
	v_mov_b32_dpp v98, v57 row_ror:15 row_mask:0xf bank_mask:0xf bound_ctrl:1
	v_pk_mul_f32 v[48:49], v[48:49], v[86:87] op_sel_hi:[1,0]
	v_pk_fma_f32 v[56:57], v[72:73], v[56:57], v[68:69]
	v_cndmask_b32_e64 v69, v100, v85, s[4:5]
	v_cndmask_b32_e64 v68, v99, v83, s[4:5]
	v_mov_b32_e32 v90, v70
	v_mov_b32_e32 v91, v66
	v_mov_b32_dpp v66, v60 row_ror:15 row_mask:0xf bank_mask:0xf bound_ctrl:1
	v_mov_b32_dpp v70, v61 row_ror:15 row_mask:0xf bank_mask:0xf bound_ctrl:1
	v_mov_b32_dpp v103, v48 row_ror:1 row_mask:0xf bank_mask:0xf bound_ctrl:1
	v_mov_b32_dpp v104, v49 row_ror:1 row_mask:0xf bank_mask:0xf bound_ctrl:1
	v_pk_fma_f32 v[68:69], v[92:93], v[68:69], v[74:75]
	v_mov_b32_e32 v94, v78
	v_mov_b32_dpp v101, v52 row_ror:15 row_mask:0xf bank_mask:0xf bound_ctrl:1
	v_mov_b32_dpp v102, v53 row_ror:15 row_mask:0xf bank_mask:0xf bound_ctrl:1
	v_cndmask_b32_e64 v79, v70, v98, s[6:7]
	v_cndmask_b32_e64 v78, v66, v87, s[6:7]
	v_pk_fma_f32 v[60:61], v[72:73], v[60:61], v[96:97]
	v_pk_fma_f32 v[52:53], v[72:73], v[52:53], v[68:69]
	v_cndmask_b32_e64 v69, v104, v100, s[4:5]
	v_cndmask_b32_e64 v68, v103, v99, s[4:5]
	v_mov_b32_dpp v76, v48 row_ror:15 row_mask:0xf bank_mask:0xf bound_ctrl:1
	v_mov_b32_dpp v77, v49 row_ror:15 row_mask:0xf bank_mask:0xf bound_ctrl:1
	v_pk_fma_f32 v[60:61], v[94:95], v[78:79], v[60:61]
	v_cndmask_b32_e64 v79, v98, v102, s[6:7]
	v_cndmask_b32_e64 v78, v87, v101, s[6:7]
	v_pk_fma_f32 v[68:69], v[92:93], v[68:69], v[74:75]
	v_pk_mul_f32 v[44:45], v[82:83], v[44:45] op_sel_hi:[0,1]
	v_pk_mul_f32 v[40:41], v[40:41], v[80:81] op_sel_hi:[1,0]
	v_pk_fma_f32 v[56:57], v[94:95], v[78:79], v[56:57]
	v_cndmask_b32_e64 v79, v102, v77, s[6:7]
	v_cndmask_b32_e64 v78, v101, v76, s[6:7]
	v_pk_fma_f32 v[48:49], v[72:73], v[48:49], v[68:69]
	v_mov_b32_dpp v68, v44 row_ror:1 row_mask:0xf bank_mask:0xf bound_ctrl:1
	v_mov_b32_dpp v69, v45 row_ror:1 row_mask:0xf bank_mask:0xf bound_ctrl:1
	v_mov_b32_dpp v85, v40 row_ror:15 row_mask:0xf bank_mask:0xf bound_ctrl:1
	v_mov_b32_e32 v66, v71
	v_pk_fma_f32 v[52:53], v[94:95], v[78:79], v[52:53]
	v_mov_b32_dpp v70, v44 row_ror:15 row_mask:0xf bank_mask:0xf bound_ctrl:1
	v_mov_b32_dpp v78, v45 row_ror:15 row_mask:0xf bank_mask:0xf bound_ctrl:1
	v_mov_b32_dpp v87, v41 row_ror:15 row_mask:0xf bank_mask:0xf bound_ctrl:1
	v_pk_mul_f32 v[72:73], v[36:37], v[84:85] op_sel_hi:[1,0]
	v_pk_fma_f32 v[36:37], v[88:89], v[68:69], v[66:67]
	v_pk_mul_f32 v[74:75], v[32:33], v[86:87] op_sel_hi:[1,0]
	v_cndmask_b32_e64 v33, v78, v87, s[6:7]
	v_cndmask_b32_e64 v32, v70, v85, s[6:7]
	v_pk_fma_f32 v[36:37], v[64:65], v[44:45], v[36:37]
	v_pk_fma_f32 v[48:49], v[94:95], v[76:77], v[48:49]
	v_pk_fma_f32 v[32:33], v[90:91], v[32:33], v[36:37]
	v_mov_b32_dpp v79, v40 row_ror:1 row_mask:0xf bank_mask:0xf bound_ctrl:1
	v_exp_f32_e64 v36, -v32
	v_exp_f32_e64 v37, -v33
	v_mov_b32_dpp v83, v41 row_ror:1 row_mask:0xf bank_mask:0xf bound_ctrl:1
	v_pk_mul_f32 v[32:33], v[60:61], v[32:33]
	v_mov_b32_dpp v94, v72 row_ror:15 row_mask:0xf bank_mask:0xf bound_ctrl:1
	v_mov_b32_dpp v95, v73 row_ror:15 row_mask:0xf bank_mask:0xf bound_ctrl:1
	v_pk_add_f32 v[36:37], v[36:37], 1.0 op_sel_hi:[1,0]
	v_cndmask_b32_e64 v45, v87, v95, s[6:7]
	v_rcp_f32_e32 v36, v36
	v_rcp_f32_e32 v37, v37
	v_cndmask_b32_e64 v44, v85, v94, s[6:7]
	v_mov_b32_dpp v92, v72 row_ror:1 row_mask:0xf bank_mask:0xf bound_ctrl:1
	v_mov_b32_dpp v93, v73 row_ror:1 row_mask:0xf bank_mask:0xf bound_ctrl:1
	v_pk_mul_f32 v[32:33], v[32:33], v[36:37]
	v_cndmask_b32_e64 v37, v83, v69, s[4:5]
	v_cndmask_b32_e64 v36, v79, v68, s[4:5]
	v_pk_fma_f32 v[36:37], v[88:89], v[36:37], v[66:67]
	v_mov_b32_dpp v76, v74 row_ror:15 row_mask:0xf bank_mask:0xf bound_ctrl:1
	v_pk_fma_f32 v[36:37], v[64:65], v[40:41], v[36:37]
	v_mov_b32_dpp v77, v75 row_ror:15 row_mask:0xf bank_mask:0xf bound_ctrl:1
	v_pk_fma_f32 v[36:37], v[90:91], v[44:45], v[36:37]
	v_cndmask_b32_e64 v45, v95, v77, s[6:7]
	v_exp_f32_e64 v40, -v36
	v_exp_f32_e64 v41, -v37
	v_pk_mul_f32 v[36:37], v[56:57], v[36:37]
	v_cndmask_b32_e64 v44, v94, v76, s[6:7]
	v_mov_b32_dpp v96, v74 row_ror:1 row_mask:0xf bank_mask:0xf bound_ctrl:1
	v_mov_b32_dpp v97, v75 row_ror:1 row_mask:0xf bank_mask:0xf bound_ctrl:1
	v_pk_add_f32 v[40:41], v[40:41], 1.0 op_sel_hi:[1,0]
	v_cvt_pk_bf16_f32 v32, v32, v33
	v_rcp_f32_e32 v40, v40
	v_rcp_f32_e32 v41, v41
	s_nop 0
	v_pk_mul_f32 v[36:37], v[36:37], v[40:41]
	v_cndmask_b32_e64 v41, v93, v83, s[4:5]
	v_cndmask_b32_e64 v40, v92, v79, s[4:5]
	v_pk_fma_f32 v[40:41], v[88:89], v[40:41], v[66:67]
	v_cvt_pk_bf16_f32 v36, v36, v37
	v_pk_fma_f32 v[40:41], v[64:65], v[72:73], v[40:41]
	s_nop 0
	v_pk_fma_f32 v[40:41], v[90:91], v[44:45], v[40:41]
	s_nop 0
	v_exp_f32_e64 v44, -v40
	v_exp_f32_e64 v45, -v41
	v_pk_mul_f32 v[40:41], v[52:53], v[40:41]
	s_nop 0
	v_pk_add_f32 v[44:45], v[44:45], 1.0 op_sel_hi:[1,0]
	s_nop 0
	v_rcp_f32_e32 v44, v44
	v_rcp_f32_e32 v45, v45
	s_nop 0
	v_pk_mul_f32 v[40:41], v[40:41], v[44:45]
	v_cndmask_b32_e64 v45, v97, v93, s[4:5]
	v_cndmask_b32_e64 v44, v96, v92, s[4:5]
	v_pk_fma_f32 v[44:45], v[88:89], v[44:45], v[66:67]
	v_cvt_pk_bf16_f32 v40, v40, v41
	v_pk_fma_f32 v[44:45], v[64:65], v[74:75], v[44:45]
	s_nop 0
	v_pk_fma_f32 v[44:45], v[90:91], v[76:77], v[44:45]
	s_nop 0
	v_exp_f32_e64 v52, -v44
	v_exp_f32_e64 v53, -v45
	v_pk_mul_f32 v[44:45], v[48:49], v[44:45]
	s_nop 0
	v_pk_add_f32 v[52:53], v[52:53], 1.0 op_sel_hi:[1,0]
	s_nop 0
	v_rcp_f32_e32 v52, v52
	v_rcp_f32_e32 v53, v53
	s_nop 0
	v_pk_mul_f32 v[44:45], v[44:45], v[52:53]
	s_nop 0
	v_cvt_pk_bf16_f32 v44, v44, v45
	global_load_dwordx4 v[68:71], v[170:171], off offset:80
	global_load_dwordx4 v[64:67], v[170:171], off offset:112
	global_load_dwordx4 v[72:75], v[170:171], off offset:64
	global_load_dwordx4 v[76:79], v[170:171], off offset:96
	s_waitcnt vmcnt(3)
; __device__ __forceinline__ unsigned cvtpk(float lo, float hi) { f32x2 v = {lo, hi}; bf16x2_t b = __builtin_convertvector(v, bf16x2_t); return __builtin_bit_cast(unsigned, b); }
; __device__ __forceinline__ float dpp_ror1(float x) { return __builtin_bit_cast(float, __builtin_amdgcn_mov_dpp(__builtin_bit_cast(int, x), 0x121, 0xF, 0xF, true)); }
; __device__ __forceinline__ float dpp_ror15(float x) { return __builtin_bit_cast(float, __builtin_amdgcn_mov_dpp(__builtin_bit_cast(int, x), 0x12F, 0xF, 0xF, true)); }
;     __device__ __forceinline__ void operator()(const f32x4 (&acc)[2][2][4][2], const Unit& u, int wr, int wc, int fr, int fq) const {
;     ...
;                         for (int m = 0; m < 4; ++m) { uv[m] = uv[m] * rs[m]; rv[m] = (f32x2){dpp_ror1(uv[m][0]), dpp_ror1(uv[m][1])}; lv[m] = (f32x2){dpp_ror15(uv[m][0]), dpp_ror15(uv[m][1])}; }
; #pragma unroll
;                         for (int m = 0; m < 4; ++m) { const f32x2 pv_ = (m > 0 && f0) ? rv[m > 0 ? m - 1 : 0] : rv[m], nv_ = (m < 3 && f15) ? lv[m < 3 ? m + 1 : 3] : lv[m];
;                             cv[m] = bv + wv0 * pv_ + wv1 * uv[m] + wv2 * nv_; }
;                     }
;                     asm volatile("" : "+v"(cv[0]), "+v"(cv[1]), "+v"(cv[2]), "+v"(cv[3]));
;                     {
;                         f32x2 rg[4], lg[4];
; #pragma unroll
;                         for (int m = 0; m < 4; ++m) { ug[m] = ug[m] * rs[m]; rg[m] = (f32x2){dpp_ror1(ug[m][0]), dpp_ror1(ug[m][1])}; lg[m] = (f32x2){dpp_ror15(ug[m][0]), dpp_ror15(ug[m][1])}; }
; #pragma unroll
;                         for (int m = 0; m < 4; ++m) { const f32x2 pg_ = (m > 0 && f0) ? rg[m > 0 ? m - 1 : 0] : rg[m], ng_ = (m < 3 && f15) ? lg[m < 3 ? m + 1 : 3] : lg[m];
;                             const f32x2 cgt = bg + wg0 * pg_ + wg1 * ug[m] + wg2 * ng_;
;                             const f32x2 e = cgt * (-LOG2E);
;                             const f32x2 d = (f32x2){__builtin_amdgcn_exp2f(e[0]), __builtin_amdgcn_exp2f(e[1])} + 1.f;
;                             const f32x2 sg = {__builtin_amdgcn_rcpf(d[0]), __builtin_amdgcn_rcpf(d[1])};
;                             const f32x2 ov = cv[m] * cgt * sg;
;                             outw[m][n][jp] = cvtpk(ov[0], ov[1]); }
	v_mov_b32_e32 v52, v68
	v_pk_mul_f32 v[56:57], v[82:83], v[62:63] op_sel_hi:[0,1]
	s_waitcnt vmcnt(1)
	v_mov_b32_e32 v60, v72
	s_waitcnt vmcnt(0)
	v_mov_b32_e32 v61, v76
	v_mov_b32_e32 v89, v78
	v_mov_b32_e32 v53, v64
	v_mov_b32_e32 v64, v69
	v_mov_b32_dpp v62, v56 row_ror:1 row_mask:0xf bank_mask:0xf bound_ctrl:1
	v_mov_b32_dpp v63, v57 row_ror:1 row_mask:0xf bank_mask:0xf bound_ctrl:1
	v_pk_mul_f32 v[68:69], v[80:81], v[58:59] op_sel_hi:[0,1]
	v_mov_b32_e32 v78, v75
	v_mov_b32_e32 v88, v74
	v_mov_b32_e32 v48, v70
	v_mov_b32_e32 v49, v66
	v_mov_b32_e32 v76, v73
	v_mov_b32_dpp v33, v56 row_ror:15 row_mask:0xf bank_mask:0xf bound_ctrl:1
	v_mov_b32_dpp v37, v57 row_ror:15 row_mask:0xf bank_mask:0xf bound_ctrl:1
	v_mov_b32_dpp v66, v68 row_ror:15 row_mask:0xf bank_mask:0xf bound_ctrl:1
	v_mov_b32_dpp v70, v69 row_ror:15 row_mask:0xf bank_mask:0xf bound_ctrl:1
	v_pk_fma_f32 v[74:75], v[60:61], v[62:63], v[78:79]
	v_mov_b32_dpp v41, v68 row_ror:1 row_mask:0xf bank_mask:0xf bound_ctrl:1
	v_mov_b32_dpp v45, v69 row_ror:1 row_mask:0xf bank_mask:0xf bound_ctrl:1
	v_cndmask_b32_e64 v59, v37, v70, s[6:7]
	v_cndmask_b32_e64 v58, v33, v66, s[6:7]
	v_pk_fma_f32 v[56:57], v[76:77], v[56:57], v[74:75]
	v_pk_mul_f32 v[54:55], v[84:85], v[54:55] op_sel_hi:[0,1]
	v_pk_fma_f32 v[58:59], v[88:89], v[58:59], v[56:57]
	v_cndmask_b32_e64 v57, v45, v63, s[4:5]
	v_cndmask_b32_e64 v56, v41, v62, s[4:5]
	v_mov_b32_dpp v87, v54 row_ror:15 row_mask:0xf bank_mask:0xf bound_ctrl:1
	v_mov_b32_dpp v90, v55 row_ror:15 row_mask:0xf bank_mask:0xf bound_ctrl:1
	v_pk_fma_f32 v[56:57], v[60:61], v[56:57], v[78:79]
	v_mov_b32_dpp v83, v54 row_ror:1 row_mask:0xf bank_mask:0xf bound_ctrl:1
	v_mov_b32_dpp v85, v55 row_ror:1 row_mask:0xf bank_mask:0xf bound_ctrl:1
	v_cndmask_b32_e64 v63, v70, v90, s[6:7]
	v_cndmask_b32_e64 v62, v66, v87, s[6:7]
	v_pk_fma_f32 v[56:57], v[76:77], v[68:69], v[56:57]
	v_pk_mul_f32 v[50:51], v[86:87], v[50:51] op_sel_hi:[0,1]
	v_pk_fma_f32 v[56:57], v[88:89], v[62:63], v[56:57]
	v_cndmask_b32_e64 v63, v85, v45, s[4:5]
	v_cndmask_b32_e64 v62, v83, v41, s[4:5]
	v_mov_b32_dpp v91, v50 row_ror:1 row_mask:0xf bank_mask:0xf bound_ctrl:1
	v_mov_b32_dpp v92, v51 row_ror:1 row_mask:0xf bank_mask:0xf bound_ctrl:1
	v_pk_fma_f32 v[62:63], v[60:61], v[62:63], v[78:79]
	v_mov_b32_dpp v72, v50 row_ror:15 row_mask:0xf bank_mask:0xf bound_ctrl:1
	v_pk_fma_f32 v[54:55], v[76:77], v[54:55], v[62:63]
	v_cndmask_b32_e64 v63, v92, v85, s[4:5]
	v_cndmask_b32_e64 v62, v91, v83, s[4:5]
	v_pk_fma_f32 v[60:61], v[60:61], v[62:63], v[78:79]
	v_mov_b32_dpp v73, v51 row_ror:15 row_mask:0xf bank_mask:0xf bound_ctrl:1
	v_pk_fma_f32 v[50:51], v[76:77], v[50:51], v[60:61]
	v_pk_mul_f32 v[60:61], v[82:83], v[46:47] op_sel_hi:[0,1]
	v_pk_mul_f32 v[42:43], v[80:81], v[42:43] op_sel_hi:[0,1]
	v_mov_b32_e32 v66, v71
	v_mov_b32_dpp v46, v60 row_ror:1 row_mask:0xf bank_mask:0xf bound_ctrl:1
	v_mov_b32_dpp v47, v61 row_ror:1 row_mask:0xf bank_mask:0xf bound_ctrl:1
	v_cndmask_b32_e64 v69, v90, v73, s[6:7]
	v_cndmask_b32_e64 v68, v87, v72, s[6:7]
	v_pk_fma_f32 v[50:51], v[88:89], v[72:73], v[50:51]
	v_mov_b32_dpp v33, v60 row_ror:15 row_mask:0xf bank_mask:0xf bound_ctrl:1
	v_mov_b32_dpp v37, v61 row_ror:15 row_mask:0xf bank_mask:0xf bound_ctrl:1
	v_mov_b32_dpp v72, v42 row_ror:15 row_mask:0xf bank_mask:0xf bound_ctrl:1
	v_mov_b32_dpp v73, v43 row_ror:15 row_mask:0xf bank_mask:0xf bound_ctrl:1
	v_pk_fma_f32 v[70:71], v[52:53], v[46:47], v[66:67]
	v_pk_fma_f32 v[54:55], v[88:89], v[68:69], v[54:55]
	v_cndmask_b32_e64 v69, v37, v73, s[6:7]
	v_cndmask_b32_e64 v68, v33, v72, s[6:7]
	v_pk_fma_f32 v[60:61], v[64:65], v[60:61], v[70:71]
	v_mov_b32_dpp v41, v42 row_ror:1 row_mask:0xf bank_mask:0xf bound_ctrl:1
	v_pk_fma_f32 v[60:61], v[48:49], v[68:69], v[60:61]
	v_mov_b32_dpp v45, v43 row_ror:1 row_mask:0xf bank_mask:0xf bound_ctrl:1
	v_exp_f32_e64 v68, -v60
	v_exp_f32_e64 v69, -v61
	v_pk_mul_f32 v[38:39], v[84:85], v[38:39] op_sel_hi:[0,1]
	v_pk_mul_f32 v[58:59], v[58:59], v[60:61]
	v_cndmask_b32_e64 v47, v45, v47, s[4:5]
	v_cndmask_b32_e64 v46, v41, v46, s[4:5]
	v_pk_add_f32 v[68:69], v[68:69], 1.0 op_sel_hi:[1,0]
	v_mov_b32_dpp v76, v38 row_ror:15 row_mask:0xf bank_mask:0xf bound_ctrl:1
	v_rcp_f32_e32 v68, v68
	v_rcp_f32_e32 v69, v69
	v_mov_b32_dpp v77, v39 row_ror:15 row_mask:0xf bank_mask:0xf bound_ctrl:1
	v_pk_fma_f32 v[46:47], v[52:53], v[46:47], v[66:67]
	v_mov_b32_dpp v74, v38 row_ror:1 row_mask:0xf bank_mask:0xf bound_ctrl:1
	v_pk_mul_f32 v[58:59], v[58:59], v[68:69]
	v_pk_fma_f32 v[42:43], v[64:65], v[42:43], v[46:47]
	v_cvt_pk_bf16_f32 v33, v58, v59
	v_cndmask_b32_e64 v59, v73, v77, s[6:7]
	v_cndmask_b32_e64 v58, v72, v76, s[6:7]
	v_pk_fma_f32 v[42:43], v[48:49], v[58:59], v[42:43]
	v_mov_b32_dpp v75, v39 row_ror:1 row_mask:0xf bank_mask:0xf bound_ctrl:1
	v_exp_f32_e64 v46, -v42
	v_exp_f32_e64 v47, -v43
	v_pk_mul_f32 v[42:43], v[56:57], v[42:43]
	v_pk_mul_f32 v[34:35], v[86:87], v[34:35] op_sel_hi:[0,1]
	v_pk_add_f32 v[46:47], v[46:47], 1.0 op_sel_hi:[1,0]
	s_nop 0
	v_rcp_f32_e32 v46, v46
	v_rcp_f32_e32 v47, v47
	v_mov_b32_dpp v62, v34 row_ror:15 row_mask:0xf bank_mask:0xf bound_ctrl:1
	v_mov_b32_dpp v63, v35 row_ror:15 row_mask:0xf bank_mask:0xf bound_ctrl:1
	v_mov_b32_dpp v78, v34 row_ror:1 row_mask:0xf bank_mask:0xf bound_ctrl:1
	v_pk_mul_f32 v[42:43], v[42:43], v[46:47]
	v_cndmask_b32_e64 v47, v77, v63, s[6:7]
	v_cvt_pk_bf16_f32 v37, v42, v43
	v_cndmask_b32_e64 v43, v75, v45, s[4:5]
	v_cndmask_b32_e64 v42, v74, v41, s[4:5]
	v_pk_fma_f32 v[42:43], v[52:53], v[42:43], v[66:67]
	v_cndmask_b32_e64 v46, v76, v62, s[6:7]
	v_pk_fma_f32 v[38:39], v[64:65], v[38:39], v[42:43]
	v_mov_b32_dpp v79, v35 row_ror:1 row_mask:0xf bank_mask:0xf bound_ctrl:1
	v_pk_fma_f32 v[38:39], v[48:49], v[46:47], v[38:39]
	s_nop 0
	v_exp_f32_e64 v42, -v38
	v_exp_f32_e64 v43, -v39
	v_pk_mul_f32 v[38:39], v[54:55], v[38:39]
	s_nop 0
	v_pk_add_f32 v[42:43], v[42:43], 1.0 op_sel_hi:[1,0]
	s_nop 0
	v_rcp_f32_e32 v42, v42
	v_rcp_f32_e32 v43, v43
	s_nop 0
	v_pk_mul_f32 v[38:39], v[38:39], v[42:43]
	s_nop 0
	v_cvt_pk_bf16_f32 v41, v38, v39
	v_cndmask_b32_e64 v39, v79, v75, s[4:5]
	v_cndmask_b32_e64 v38, v78, v74, s[4:5]
	v_pk_fma_f32 v[38:39], v[52:53], v[38:39], v[66:67]
	s_nop 0
	v_pk_fma_f32 v[34:35], v[64:65], v[34:35], v[38:39]
	s_nop 0
	v_pk_fma_f32 v[34:35], v[48:49], v[62:63], v[34:35]
	s_nop 0
	v_exp_f32_e64 v38, -v34
	v_exp_f32_e64 v39, -v35
	v_pk_mul_f32 v[34:35], v[50:51], v[34:35]
	s_nop 0
	v_pk_add_f32 v[38:39], v[38:39], 1.0 op_sel_hi:[1,0]
	s_nop 0
	v_rcp_f32_e32 v38, v38
	v_rcp_f32_e32 v39, v39
	s_nop 0
	v_pk_mul_f32 v[34:35], v[34:35], v[38:39]
	s_nop 0
	v_cvt_pk_bf16_f32 v45, v34, v35
	global_load_dwordx4 v[50:53], v[170:171], off offset:144
	global_load_dwordx4 v[46:49], v[170:171], off offset:176
	global_load_dwordx4 v[58:61], v[170:171], off offset:128
	global_load_dwordx4 v[62:65], v[170:171], off offset:160
	s_waitcnt vmcnt(3)
; __device__ __forceinline__ unsigned cvtpk(float lo, float hi) { f32x2 v = {lo, hi}; bf16x2_t b = __builtin_convertvector(v, bf16x2_t); return __builtin_bit_cast(unsigned, b); }
; __device__ __forceinline__ float dpp_ror1(float x) { return __builtin_bit_cast(float, __builtin_amdgcn_mov_dpp(__builtin_bit_cast(int, x), 0x121, 0xF, 0xF, true)); }
; __device__ __forceinline__ float dpp_ror15(float x) { return __builtin_bit_cast(float, __builtin_amdgcn_mov_dpp(__builtin_bit_cast(int, x), 0x12F, 0xF, 0xF, true)); }
;     __device__ __forceinline__ void operator()(const f32x4 (&acc)[2][2][4][2], const Unit& u, int wr, int wc, int fr, int fq) const {
;     ...
;                         for (int m = 0; m < 4; ++m) { uv[m] = uv[m] * rs[m]; rv[m] = (f32x2){dpp_ror1(uv[m][0]), dpp_ror1(uv[m][1])}; lv[m] = (f32x2){dpp_ror15(uv[m][0]), dpp_ror15(uv[m][1])}; }
; #pragma unroll
;                         for (int m = 0; m < 4; ++m) { const f32x2 pv_ = (m > 0 && f0) ? rv[m > 0 ? m - 1 : 0] : rv[m], nv_ = (m < 3 && f15) ? lv[m < 3 ? m + 1 : 3] : lv[m];
;                             cv[m] = bv + wv0 * pv_ + wv1 * uv[m] + wv2 * nv_; }
;                     }
;                     asm volatile("" : "+v"(cv[0]), "+v"(cv[1]), "+v"(cv[2]), "+v"(cv[3]));
;                     {
;                         f32x2 rg[4], lg[4];
; #pragma unroll
;                         for (int m = 0; m < 4; ++m) { ug[m] = ug[m] * rs[m]; rg[m] = (f32x2){dpp_ror1(ug[m][0]), dpp_ror1(ug[m][1])}; lg[m] = (f32x2){dpp_ror15(ug[m][0]), dpp_ror15(ug[m][1])}; }
; #pragma unroll
;                         for (int m = 0; m < 4; ++m) { const f32x2 pg_ = (m > 0 && f0) ? rg[m > 0 ? m - 1 : 0] : rg[m], ng_ = (m < 3 && f15) ? lg[m < 3 ? m + 1 : 3] : lg[m];
;                             const f32x2 cgt = bg + wg0 * pg_ + wg1 * ug[m] + wg2 * ng_;
;                             const f32x2 e = cgt * (-LOG2E);
;                             const f32x2 d = (f32x2){__builtin_amdgcn_exp2f(e[0]), __builtin_amdgcn_exp2f(e[1])} + 1.f;
;                             const f32x2 sg = {__builtin_amdgcn_rcpf(d[0]), __builtin_amdgcn_rcpf(d[1])};
;                             const f32x2 ov = cv[m] * cgt * sg;
;                             outw[m][n][jp] = cvtpk(ov[0], ov[1]); }
	v_mov_b32_e32 v54, v52
	v_pk_mul_f32 v[28:29], v[82:83], v[28:29] op_sel_hi:[0,1]
	v_pk_mul_f32 v[24:25], v[80:81], v[24:25] op_sel_hi:[0,1]
	s_waitcnt vmcnt(1)
	v_mov_b32_e32 v34, v58
	s_waitcnt vmcnt(0)
	v_mov_b32_e32 v35, v62
	v_mov_b32_e32 v39, v64
	v_mov_b32_dpp v42, v28 row_ror:1 row_mask:0xf bank_mask:0xf bound_ctrl:1
	v_mov_b32_dpp v43, v29 row_ror:1 row_mask:0xf bank_mask:0xf bound_ctrl:1
	v_mov_b32_dpp v66, v24 row_ror:1 row_mask:0xf bank_mask:0xf bound_ctrl:1
	v_mov_b32_dpp v67, v25 row_ror:1 row_mask:0xf bank_mask:0xf bound_ctrl:1
	v_mov_b32_e32 v64, v61
	v_mov_b32_e32 v38, v60
	v_pk_mul_f32 v[20:21], v[84:85], v[20:21] op_sel_hi:[0,1]
	v_pk_fma_f32 v[60:61], v[34:35], v[42:43], v[64:65]
	v_cndmask_b32_e64 v43, v67, v43, s[4:5]
	v_cndmask_b32_e64 v42, v66, v42, s[4:5]
	v_mov_b32_e32 v62, v59
	v_mov_b32_dpp v70, v20 row_ror:1 row_mask:0xf bank_mask:0xf bound_ctrl:1
	v_mov_b32_dpp v71, v21 row_ror:1 row_mask:0xf bank_mask:0xf bound_ctrl:1
	v_pk_fma_f32 v[42:43], v[34:35], v[42:43], v[64:65]
	v_mov_b32_dpp v68, v24 row_ror:15 row_mask:0xf bank_mask:0xf bound_ctrl:1
	v_mov_b32_dpp v69, v25 row_ror:15 row_mask:0xf bank_mask:0xf bound_ctrl:1
	v_pk_mul_f32 v[16:17], v[86:87], v[16:17] op_sel_hi:[0,1]
	v_pk_fma_f32 v[24:25], v[62:63], v[24:25], v[42:43]
	v_cndmask_b32_e64 v43, v71, v67, s[4:5]
	v_cndmask_b32_e64 v42, v70, v66, s[4:5]
	v_mov_b32_dpp v74, v16 row_ror:1 row_mask:0xf bank_mask:0xf bound_ctrl:1
	v_mov_b32_dpp v75, v17 row_ror:1 row_mask:0xf bank_mask:0xf bound_ctrl:1
	v_pk_fma_f32 v[42:43], v[34:35], v[42:43], v[64:65]
	v_mov_b32_e32 v55, v48
	v_mov_b32_dpp v48, v28 row_ror:15 row_mask:0xf bank_mask:0xf bound_ctrl:1
	v_mov_b32_dpp v52, v29 row_ror:15 row_mask:0xf bank_mask:0xf bound_ctrl:1
	v_mov_b32_dpp v72, v20 row_ror:15 row_mask:0xf bank_mask:0xf bound_ctrl:1
	v_mov_b32_dpp v73, v21 row_ror:15 row_mask:0xf bank_mask:0xf bound_ctrl:1
	v_pk_fma_f32 v[20:21], v[62:63], v[20:21], v[42:43]
	v_cndmask_b32_e64 v43, v75, v71, s[4:5]
	v_cndmask_b32_e64 v42, v74, v70, s[4:5]
	v_cndmask_b32_e64 v59, v52, v69, s[6:7]
	v_cndmask_b32_e64 v58, v48, v68, s[6:7]
	v_pk_fma_f32 v[28:29], v[62:63], v[28:29], v[60:61]
	v_pk_fma_f32 v[34:35], v[34:35], v[42:43], v[64:65]
	v_mov_b32_e32 v56, v50
	v_mov_b32_e32 v57, v46
	v_mov_b32_e32 v46, v51
	v_mov_b32_dpp v50, v16 row_ror:15 row_mask:0xf bank_mask:0xf bound_ctrl:1
	v_mov_b32_dpp v51, v17 row_ror:15 row_mask:0xf bank_mask:0xf bound_ctrl:1
	v_pk_fma_f32 v[28:29], v[38:39], v[58:59], v[28:29]
	v_cndmask_b32_e64 v59, v69, v73, s[6:7]
	v_cndmask_b32_e64 v58, v68, v72, s[6:7]
	v_pk_fma_f32 v[16:17], v[62:63], v[16:17], v[34:35]
	v_pk_mul_f32 v[34:35], v[82:83], v[12:13] op_sel_hi:[0,1]
	v_pk_fma_f32 v[24:25], v[38:39], v[58:59], v[24:25]
	v_cndmask_b32_e64 v59, v73, v51, s[6:7]
	v_cndmask_b32_e64 v58, v72, v50, s[6:7]
	v_mov_b32_dpp v12, v34 row_ror:1 row_mask:0xf bank_mask:0xf bound_ctrl:1
	v_mov_b32_dpp v13, v35 row_ror:1 row_mask:0xf bank_mask:0xf bound_ctrl:1
	v_pk_mul_f32 v[8:9], v[80:81], v[8:9] op_sel_hi:[0,1]
	v_mov_b32_e32 v48, v53
	v_pk_fma_f32 v[20:21], v[38:39], v[58:59], v[20:21]
	v_pk_fma_f32 v[16:17], v[38:39], v[50:51], v[16:17]
	v_mov_b32_dpp v38, v34 row_ror:15 row_mask:0xf bank_mask:0xf bound_ctrl:1
	v_mov_b32_dpp v39, v35 row_ror:15 row_mask:0xf bank_mask:0xf bound_ctrl:1
	v_mov_b32_dpp v59, v8 row_ror:15 row_mask:0xf bank_mask:0xf bound_ctrl:1
	v_mov_b32_dpp v60, v9 row_ror:15 row_mask:0xf bank_mask:0xf bound_ctrl:1
	v_pk_fma_f32 v[42:43], v[56:57], v[12:13], v[48:49]
	v_cndmask_b32_e64 v39, v39, v60, s[6:7]
	v_cndmask_b32_e64 v38, v38, v59, s[6:7]
	v_pk_fma_f32 v[34:35], v[46:47], v[34:35], v[42:43]
	v_mov_b32_dpp v52, v8 row_ror:1 row_mask:0xf bank_mask:0xf bound_ctrl:1
	v_pk_fma_f32 v[34:35], v[54:55], v[38:39], v[34:35]
	v_mov_b32_dpp v58, v9 row_ror:1 row_mask:0xf bank_mask:0xf bound_ctrl:1
	v_exp_f32_e64 v38, -v34
	v_exp_f32_e64 v39, -v35
	v_pk_mul_f32 v[4:5], v[84:85], v[4:5] op_sel_hi:[0,1]
	v_pk_mul_f32 v[28:29], v[28:29], v[34:35]
	v_cndmask_b32_e64 v13, v58, v13, s[4:5]
	v_cndmask_b32_e64 v12, v52, v12, s[4:5]
	v_pk_add_f32 v[38:39], v[38:39], 1.0 op_sel_hi:[1,0]
	v_mov_b32_dpp v63, v4 row_ror:15 row_mask:0xf bank_mask:0xf bound_ctrl:1
	v_rcp_f32_e32 v38, v38
	v_rcp_f32_e32 v39, v39
	v_mov_b32_dpp v64, v5 row_ror:15 row_mask:0xf bank_mask:0xf bound_ctrl:1
	v_pk_fma_f32 v[12:13], v[56:57], v[12:13], v[48:49]
	v_mov_b32_dpp v61, v4 row_ror:1 row_mask:0xf bank_mask:0xf bound_ctrl:1
	v_pk_mul_f32 v[28:29], v[28:29], v[38:39]
	v_pk_fma_f32 v[8:9], v[46:47], v[8:9], v[12:13]
	v_cvt_pk_bf16_f32 v34, v28, v29
	v_cndmask_b32_e64 v29, v60, v64, s[6:7]
	v_cndmask_b32_e64 v28, v59, v63, s[6:7]
	v_pk_fma_f32 v[8:9], v[54:55], v[28:29], v[8:9]
	v_mov_b32_dpp v62, v5 row_ror:1 row_mask:0xf bank_mask:0xf bound_ctrl:1
	v_exp_f32_e64 v12, -v8
	v_exp_f32_e64 v13, -v9
	v_pk_mul_f32 v[8:9], v[24:25], v[8:9]
	v_pk_mul_f32 v[0:1], v[86:87], v[0:1] op_sel_hi:[0,1]
	v_pk_add_f32 v[12:13], v[12:13], 1.0 op_sel_hi:[1,0]
	s_nop 0
	v_rcp_f32_e32 v12, v12
	v_rcp_f32_e32 v13, v13
	v_mov_b32_dpp v50, v0 row_ror:15 row_mask:0xf bank_mask:0xf bound_ctrl:1
	v_mov_b32_dpp v51, v1 row_ror:15 row_mask:0xf bank_mask:0xf bound_ctrl:1
	v_mov_b32_dpp v65, v0 row_ror:1 row_mask:0xf bank_mask:0xf bound_ctrl:1
	v_pk_mul_f32 v[8:9], v[8:9], v[12:13]
	v_cndmask_b32_e64 v13, v64, v51, s[6:7]
	v_cvt_pk_bf16_f32 v38, v8, v9
	v_cndmask_b32_e64 v9, v62, v58, s[4:5]
	v_cndmask_b32_e64 v8, v61, v52, s[4:5]
	v_pk_fma_f32 v[8:9], v[56:57], v[8:9], v[48:49]
	v_cndmask_b32_e64 v12, v63, v50, s[6:7]
	v_pk_fma_f32 v[4:5], v[46:47], v[4:5], v[8:9]
	v_mov_b32_dpp v66, v1 row_ror:1 row_mask:0xf bank_mask:0xf bound_ctrl:1
	v_pk_fma_f32 v[4:5], v[54:55], v[12:13], v[4:5]
	s_nop 0
	v_exp_f32_e64 v8, -v4
	v_exp_f32_e64 v9, -v5
	v_pk_mul_f32 v[4:5], v[20:21], v[4:5]
	s_nop 0
	v_pk_add_f32 v[8:9], v[8:9], 1.0 op_sel_hi:[1,0]
	s_nop 0
	v_rcp_f32_e32 v8, v8
	v_rcp_f32_e32 v9, v9
	s_nop 0
	v_pk_mul_f32 v[4:5], v[4:5], v[8:9]
	s_nop 0
	v_cvt_pk_bf16_f32 v42, v4, v5
	v_cndmask_b32_e64 v5, v66, v62, s[4:5]
	v_cndmask_b32_e64 v4, v65, v61, s[4:5]
	v_pk_fma_f32 v[4:5], v[56:57], v[4:5], v[48:49]
	s_nop 0
	v_pk_fma_f32 v[0:1], v[46:47], v[0:1], v[4:5]
	s_nop 0
	v_pk_fma_f32 v[0:1], v[54:55], v[50:51], v[0:1]
	s_nop 0
	v_exp_f32_e64 v4, -v0
	v_exp_f32_e64 v5, -v1
	v_pk_mul_f32 v[0:1], v[16:17], v[0:1]
	s_nop 0
	v_pk_add_f32 v[4:5], v[4:5], 1.0 op_sel_hi:[1,0]
	s_nop 0
	v_rcp_f32_e32 v4, v4
	v_rcp_f32_e32 v5, v5
	s_nop 0
	v_pk_mul_f32 v[0:1], v[0:1], v[4:5]
	s_nop 0
	v_cvt_pk_bf16_f32 v46, v0, v1
	global_load_dwordx4 v[52:55], v[170:171], off offset:192
	global_load_dwordx4 v[56:59], v[170:171], off offset:224
	global_load_dwordx4 v[60:63], v[170:171], off offset:208
	global_load_dwordx4 v[48:51], v[170:171], off offset:240
	s_waitcnt vmcnt(3)
;     __device__ __forceinline__ void operator()(const f32x4 (&acc)[2][2][4][2], const Unit& u, int wr, int wc, int fr, int fq) const {
;     ...
;                         for (int m = 0; m < 4; ++m) { uv[m] = uv[m] * rs[m]; rv[m] = (f32x2){dpp_ror1(uv[m][0]), dpp_ror1(uv[m][1])}; lv[m] = (f32x2){dpp_ror15(uv[m][0]), dpp_ror15(uv[m][1])}; }
; #pragma unroll
;                         for (int m = 0; m < 4; ++m) { const f32x2 pv_ = (m > 0 && f0) ? rv[m > 0 ? m - 1 : 0] : rv[m], nv_ = (m < 3 && f15) ? lv[m < 3 ? m + 1 : 3] : lv[m];
;                             cv[m] = bv + wv0 * pv_ + wv1 * uv[m] + wv2 * nv_; }
;                     }
;                     asm volatile("" : "+v"(cv[0]), "+v"(cv[1]), "+v"(cv[2]), "+v"(cv[3]));
;                     {
;                         f32x2 rg[4], lg[4];
; #pragma unroll
;                         for (int m = 0; m < 4; ++m) { ug[m] = ug[m] * rs[m]; rg[m] = (f32x2){dpp_ror1(ug[m][0]), dpp_ror1(ug[m][1])}; lg[m] = (f32x2){dpp_ror15(ug[m][0]), dpp_ror15(ug[m][1])}; }
; #pragma unroll
;                         for (int m = 0; m < 4; ++m) { const f32x2 pg_ = (m > 0 && f0) ? rg[m > 0 ? m - 1 : 0] : rg[m], ng_ = (m < 3 && f15) ? lg[m < 3 ? m + 1 : 3] : lg[m];
;                             const f32x2 cgt = bg + wg0 * pg_ + wg1 * ug[m] + wg2 * ng_;
;                             const f32x2 e = cgt * (-LOG2E);
;                             const f32x2 d = (f32x2){__builtin_amdgcn_exp2f(e[0]), __builtin_amdgcn_exp2f(e[1])} + 1.f;
;                             const f32x2 sg = {__builtin_amdgcn_rcpf(d[0]), __builtin_amdgcn_rcpf(d[1])};
;                             const f32x2 ov = cv[m] * cgt * sg;
;                             outw[m][n][jp] = cvtpk(ov[0], ov[1]); }
;                     }
;                     asm volatile("" : "+v"(outw[0][n][jp]), "+v"(outw[1][n][jp]), "+v"(outw[2][n][jp]), "+v"(outw[3][n][jp]) :: "memory"); __builtin_amdgcn_sched_barrier(0);
;                 }
; #pragma unroll
;             for (int m = 0; m < 4; ++m) { const int i = 16 * m + fr, t = tbase + i;
;                 if (i >= 1 && i <= 62 && t < slen) { u32x4 w; w.x = outw[m][0][0]; w.y = outw[m][0][1]; w.z = outw[m][1][0]; w.w = outw[m][1][1];
;                     *(u32x4*)(Gout + (size_t)(seqbase + t) * DFF + 128 * u.pn + 32 * wc + 8 * fq) = w; } }
	v_mov_b32_e32 v70, v54
	v_pk_mul_f32 v[14:15], v[82:83], v[14:15] op_sel_hi:[0,1]
	v_pk_mul_f32 v[10:11], v[80:81], v[10:11] op_sel_hi:[0,1]
	s_waitcnt vmcnt(1)
	v_mov_b32_e32 v72, v60
	v_mov_b32_dpp v20, v14 row_ror:1 row_mask:0xf bank_mask:0xf bound_ctrl:1
	v_mov_b32_dpp v21, v15 row_ror:1 row_mask:0xf bank_mask:0xf bound_ctrl:1
	s_waitcnt vmcnt(0)
	v_mov_b32_e32 v73, v48
	v_mov_b32_e32 v75, v50
	v_mov_b32_e32 v50, v63
	v_pk_mul_f32 v[0:1], v[82:83], v[30:31] op_sel_hi:[0,1]
	v_pk_mul_f32 v[4:5], v[80:81], v[26:27] op_sel_hi:[0,1]
	v_mov_b32_dpp v66, v14 row_ror:15 row_mask:0xf bank_mask:0xf bound_ctrl:1
	v_mov_b32_dpp v67, v15 row_ror:15 row_mask:0xf bank_mask:0xf bound_ctrl:1
	v_mov_b32_dpp v78, v10 row_ror:15 row_mask:0xf bank_mask:0xf bound_ctrl:1
	v_mov_b32_dpp v79, v11 row_ror:15 row_mask:0xf bank_mask:0xf bound_ctrl:1
	v_mov_b32_e32 v71, v58
	v_mov_b32_e32 v48, v61
	v_mov_b32_e32 v58, v55
	v_pk_fma_f32 v[54:55], v[72:73], v[20:21], v[50:51]
	v_mov_b32_dpp v16, v0 row_ror:1 row_mask:0xf bank_mask:0xf bound_ctrl:1
	v_mov_b32_dpp v17, v1 row_ror:1 row_mask:0xf bank_mask:0xf bound_ctrl:1
	v_mov_b32_dpp v28, v4 row_ror:1 row_mask:0xf bank_mask:0xf bound_ctrl:1
	v_mov_b32_dpp v29, v5 row_ror:1 row_mask:0xf bank_mask:0xf bound_ctrl:1
	v_cndmask_b32_e64 v67, v67, v79, s[6:7]
	v_cndmask_b32_e64 v66, v66, v78, s[6:7]
	v_mov_b32_e32 v68, v52
	v_mov_b32_e32 v69, v56
	v_mov_b32_e32 v74, v62
	v_pk_fma_f32 v[14:15], v[48:49], v[14:15], v[54:55]
	v_cndmask_b32_e64 v25, v29, v17, s[4:5]
	v_cndmask_b32_e64 v24, v28, v16, s[4:5]
	v_mov_b32_e32 v56, v53
	v_pk_fma_f32 v[16:17], v[68:69], v[16:17], v[58:59]
	v_pk_fma_f32 v[14:15], v[74:75], v[66:67], v[14:15]
	v_pk_mul_f32 v[8:9], v[84:85], v[22:23] op_sel_hi:[0,1]
	v_mov_b32_dpp v22, v0 row_ror:15 row_mask:0xf bank_mask:0xf bound_ctrl:1
	v_mov_b32_dpp v23, v1 row_ror:15 row_mask:0xf bank_mask:0xf bound_ctrl:1
	v_pk_fma_f32 v[0:1], v[56:57], v[0:1], v[16:17]
	v_exp_f32_e64 v16, -v14
	v_exp_f32_e64 v17, -v15
	v_mov_b32_dpp v76, v10 row_ror:1 row_mask:0xf bank_mask:0xf bound_ctrl:1
	v_mov_b32_dpp v77, v11 row_ror:1 row_mask:0xf bank_mask:0xf bound_ctrl:1
	v_pk_mul_f32 v[12:13], v[86:87], v[18:19] op_sel_hi:[0,1]
	v_pk_mul_f32 v[6:7], v[84:85], v[6:7] op_sel_hi:[0,1]
	v_mov_b32_dpp v26, v4 row_ror:15 row_mask:0xf bank_mask:0xf bound_ctrl:1
	v_mov_b32_dpp v27, v5 row_ror:15 row_mask:0xf bank_mask:0xf bound_ctrl:1
	v_cndmask_b32_e64 v21, v77, v21, s[4:5]
	v_cndmask_b32_e64 v20, v76, v20, s[4:5]
	v_mov_b32_dpp v35, v8 row_ror:1 row_mask:0xf bank_mask:0xf bound_ctrl:1
	v_mov_b32_dpp v39, v9 row_ror:1 row_mask:0xf bank_mask:0xf bound_ctrl:1
	v_mov_b32_dpp v43, v12 row_ror:1 row_mask:0xf bank_mask:0xf bound_ctrl:1
	v_mov_b32_dpp v47, v13 row_ror:1 row_mask:0xf bank_mask:0xf bound_ctrl:1
	v_mov_b32_dpp v83, v6 row_ror:15 row_mask:0xf bank_mask:0xf bound_ctrl:1
	v_mov_b32_dpp v84, v7 row_ror:15 row_mask:0xf bank_mask:0xf bound_ctrl:1
	v_cndmask_b32_e64 v23, v23, v27, s[6:7]
	v_cndmask_b32_e64 v22, v22, v26, s[6:7]
	v_pk_fma_f32 v[20:21], v[72:73], v[20:21], v[50:51]
	v_cndmask_b32_e64 v29, v39, v29, s[4:5]
	v_cndmask_b32_e64 v28, v35, v28, s[4:5]
	v_cndmask_b32_e64 v65, v47, v39, s[4:5]
	v_cndmask_b32_e64 v64, v43, v35, s[4:5]
	v_pk_fma_f32 v[0:1], v[70:71], v[22:23], v[0:1]
	v_cndmask_b32_e64 v23, v79, v84, s[6:7]
	v_cndmask_b32_e64 v22, v78, v83, s[6:7]
	v_pk_fma_f32 v[10:11], v[48:49], v[10:11], v[20:21]
	v_mov_b32_dpp v30, v8 row_ror:15 row_mask:0xf bank_mask:0xf bound_ctrl:1
	v_mov_b32_dpp v31, v9 row_ror:15 row_mask:0xf bank_mask:0xf bound_ctrl:1
	v_mov_b32_dpp v18, v12 row_ror:15 row_mask:0xf bank_mask:0xf bound_ctrl:1
	v_mov_b32_dpp v19, v13 row_ror:15 row_mask:0xf bank_mask:0xf bound_ctrl:1
	v_pk_fma_f32 v[24:25], v[68:69], v[24:25], v[58:59]
	v_pk_fma_f32 v[28:29], v[68:69], v[28:29], v[58:59]
	v_pk_fma_f32 v[52:53], v[68:69], v[64:65], v[58:59]
	v_pk_add_f32 v[16:17], v[16:17], 1.0 op_sel_hi:[1,0]
	v_pk_fma_f32 v[10:11], v[74:75], v[22:23], v[10:11]
	v_cndmask_b32_e64 v27, v27, v31, s[6:7]
	v_cndmask_b32_e64 v26, v26, v30, s[6:7]
	v_cndmask_b32_e64 v31, v31, v19, s[6:7]
	v_cndmask_b32_e64 v30, v30, v18, s[6:7]
	v_pk_fma_f32 v[4:5], v[56:57], v[4:5], v[24:25]
	v_pk_fma_f32 v[8:9], v[56:57], v[8:9], v[28:29]
	v_pk_fma_f32 v[12:13], v[56:57], v[12:13], v[52:53]
	v_rcp_f32_e32 v16, v16
	v_rcp_f32_e32 v17, v17
	v_exp_f32_e64 v20, -v10
	v_exp_f32_e64 v21, -v11
	v_pk_fma_f32 v[4:5], v[70:71], v[26:27], v[4:5]
	v_pk_fma_f32 v[8:9], v[70:71], v[30:31], v[8:9]
	v_pk_fma_f32 v[12:13], v[70:71], v[18:19], v[12:13]
	v_mov_b32_dpp v80, v6 row_ror:1 row_mask:0xf bank_mask:0xf bound_ctrl:1
	v_pk_mul_f32 v[0:1], v[0:1], v[14:15]
	v_mov_b32_dpp v82, v7 row_ror:1 row_mask:0xf bank_mask:0xf bound_ctrl:1
	v_pk_mul_f32 v[0:1], v[0:1], v[16:17]
	v_pk_mul_f32 v[2:3], v[86:87], v[2:3] op_sel_hi:[0,1]
	v_cvt_pk_bf16_f32 v35, v0, v1
	v_pk_add_f32 v[0:1], v[20:21], 1.0 op_sel_hi:[1,0]
	v_cndmask_b32_e64 v15, v82, v77, s[4:5]
	v_rcp_f32_e32 v0, v0
	v_rcp_f32_e32 v1, v1
	v_cndmask_b32_e64 v14, v80, v76, s[4:5]
	v_mov_b32_dpp v85, v2 row_ror:1 row_mask:0xf bank_mask:0xf bound_ctrl:1
	v_mov_b32_dpp v24, v3 row_ror:1 row_mask:0xf bank_mask:0xf bound_ctrl:1
	v_mov_b32_dpp v18, v2 row_ror:15 row_mask:0xf bank_mask:0xf bound_ctrl:1
	v_mov_b32_dpp v19, v3 row_ror:15 row_mask:0xf bank_mask:0xf bound_ctrl:1
	v_pk_fma_f32 v[14:15], v[72:73], v[14:15], v[50:51]
	v_pk_mul_f32 v[4:5], v[4:5], v[10:11]
	v_cndmask_b32_e64 v17, v84, v19, s[6:7]
	v_cndmask_b32_e64 v16, v83, v18, s[6:7]
	v_pk_fma_f32 v[6:7], v[48:49], v[6:7], v[14:15]
	v_pk_mul_f32 v[0:1], v[4:5], v[0:1]
	v_cndmask_b32_e64 v5, v24, v82, s[4:5]
	v_cndmask_b32_e64 v4, v85, v80, s[4:5]
	v_pk_fma_f32 v[6:7], v[74:75], v[16:17], v[6:7]
	v_pk_fma_f32 v[4:5], v[72:73], v[4:5], v[50:51]
	v_exp_f32_e64 v14, -v6
	v_exp_f32_e64 v15, -v7
	v_pk_fma_f32 v[2:3], v[48:49], v[2:3], v[4:5]
	v_pk_fma_f32 v[2:3], v[74:75], v[18:19], v[2:3]
	v_cvt_pk_bf16_f32 v39, v0, v1
	v_exp_f32_e64 v4, -v2
	v_exp_f32_e64 v5, -v3
	v_pk_add_f32 v[0:1], v[14:15], 1.0 op_sel_hi:[1,0]
	v_rcp_f32_e32 v0, v0
	v_rcp_f32_e32 v1, v1
	v_pk_mul_f32 v[6:7], v[8:9], v[6:7]
	v_pk_add_f32 v[4:5], v[4:5], 1.0 op_sel_hi:[1,0]
	v_pk_mul_f32 v[0:1], v[6:7], v[0:1]
	v_rcp_f32_e32 v4, v4
	v_rcp_f32_e32 v5, v5
	v_cvt_pk_bf16_f32 v43, v0, v1
	v_pk_mul_f32 v[0:1], v[12:13], v[2:3]
	s_nop 0
	v_pk_mul_f32 v[0:1], v[0:1], v[4:5]
	s_nop 0
	v_cvt_pk_bf16_f32 v47, v0, v1
	v_cmp_gt_i32_e32 vcc, s51, v81
	s_and_b64 s[14:15], s[8:9], vcc
	s_and_saveexec_b64 s[2:3], s[14:15]
	s_cbranch_execz .LBB0_804
	v_add_u32_e32 v2, s29, v81
	v_mov_b64_e32 v[0:1], s[24:25]
	v_mad_i64_i32 v[0:1], s[14:15], v2, s73, v[0:1]
	v_lshl_add_u64 v[0:1], s[36:37], 1, v[0:1]
	s_lshl_b32 s84, s45, 1
	v_lshl_add_u64 v[0:1], v[0:1], 0, s[84:85]
	v_lshl_add_u64 v[0:1], v[0:1], 0, v[144:145]
	global_store_dwordx4 v[0:1], v[32:35], off
